# A/B of the GEMM K-loops' per-segment s_setprio flips: all 96 deleted (priority stays 0)
# speedup vs baseline: 1.0101x; 1.0004x over previous
.LBB0_447:
	v_add_u32_e32 v0, s23, v225
	ds_read_b128 v[148:151], v0
	ds_read_b128 v[152:155], v0 offset:1024
	ds_read_b128 v[156:159], v0 offset:2048
	ds_read_b128 v[160:163], v0 offset:3072
	v_add_u32_e32 v0, s50, v225
	ds_read_b128 v[132:135], v0
	ds_read_b128 v[136:139], v0 offset:1024
	ds_read_b128 v[140:143], v0 offset:2048
	ds_read_b128 v[144:147], v0 offset:3072
	v_lshl_add_u64 v[2:3], v[216:217], 0, s[28:29]
	s_add_i32 m0, s53, 0xc000
	s_waitcnt lgkmcnt(0)
	ds_read_b128 v[176:179], v241
	ds_read_b128 v[192:195], v241 offset:1024
	ds_read_b128 v[172:175], v241 offset:2048
	ds_read_b128 v[188:191], v241 offset:3072
	ds_read_b128 v[168:171], v241 offset:4096
	ds_read_b128 v[184:187], v241 offset:5120
	ds_read_b128 v[164:167], v241 offset:6144
	ds_read_b128 v[180:183], v241 offset:7168
	global_load_lds_dwordx4 v[2:3], off
	v_lshl_add_u64 v[2:3], v[214:215], 0, s[28:29]
	s_add_i32 m0, s53, 0xe000
	s_nop 0
	global_load_lds_dwordx4 v[2:3], off
	s_waitcnt vmcnt(8)
	s_waitcnt lgkmcnt(0)
	s_barrier
	s_waitcnt lgkmcnt(0)
	v_mfma_f32_16x16x32_bf16 v[128:131], v[148:151], v[176:179], v[128:131]
	v_mfma_f32_16x16x32_bf16 v[120:123], v[156:159], v[176:179], v[120:123]
	v_mfma_f32_16x16x32_bf16 v[112:115], v[148:151], v[172:175], v[112:115]
	v_mfma_f32_16x16x32_bf16 v[104:107], v[156:159], v[172:175], v[104:107]
	v_mfma_f32_16x16x32_bf16 v[96:99], v[148:151], v[168:171], v[96:99]
	v_mfma_f32_16x16x32_bf16 v[88:91], v[156:159], v[168:171], v[88:91]
	v_mfma_f32_16x16x32_bf16 v[80:83], v[148:151], v[164:167], v[80:83]
	v_mfma_f32_16x16x32_bf16 v[72:75], v[156:159], v[164:167], v[72:75]
	v_mfma_f32_16x16x32_bf16 v[128:131], v[152:155], v[192:195], v[128:131]
	v_mfma_f32_16x16x32_bf16 v[120:123], v[160:163], v[192:195], v[120:123]
	v_mfma_f32_16x16x32_bf16 v[112:115], v[152:155], v[188:191], v[112:115]
	v_mfma_f32_16x16x32_bf16 v[104:107], v[160:163], v[188:191], v[104:107]
	v_mfma_f32_16x16x32_bf16 v[96:99], v[152:155], v[184:187], v[96:99]
	v_mfma_f32_16x16x32_bf16 v[88:91], v[160:163], v[184:187], v[88:91]
	v_mfma_f32_16x16x32_bf16 v[80:83], v[152:155], v[180:183], v[80:83]
	v_mfma_f32_16x16x32_bf16 v[72:75], v[160:163], v[180:183], v[72:75]
	v_mfma_f32_16x16x32_bf16 v[124:127], v[132:135], v[176:179], v[124:127]
	v_mfma_f32_16x16x32_bf16 v[116:119], v[140:143], v[176:179], v[116:119]
	v_mfma_f32_16x16x32_bf16 v[108:111], v[132:135], v[172:175], v[108:111]
	v_mfma_f32_16x16x32_bf16 v[100:103], v[140:143], v[172:175], v[100:103]
	v_mfma_f32_16x16x32_bf16 v[92:95], v[132:135], v[168:171], v[92:95]
	v_mfma_f32_16x16x32_bf16 v[84:87], v[140:143], v[168:171], v[84:87]
	v_mfma_f32_16x16x32_bf16 v[76:79], v[132:135], v[164:167], v[76:79]
	v_mfma_f32_16x16x32_bf16 v[68:71], v[140:143], v[164:167], v[68:71]
	v_mfma_f32_16x16x32_bf16 v[124:127], v[136:139], v[192:195], v[124:127]
	v_mfma_f32_16x16x32_bf16 v[116:119], v[144:147], v[192:195], v[116:119]
	v_mfma_f32_16x16x32_bf16 v[108:111], v[136:139], v[188:191], v[108:111]
	v_mfma_f32_16x16x32_bf16 v[100:103], v[144:147], v[188:191], v[100:103]
	v_mfma_f32_16x16x32_bf16 v[92:95], v[136:139], v[184:187], v[92:95]
	v_mfma_f32_16x16x32_bf16 v[84:87], v[144:147], v[184:187], v[84:87]
	v_mfma_f32_16x16x32_bf16 v[76:79], v[136:139], v[180:183], v[76:79]
	v_mfma_f32_16x16x32_bf16 v[68:71], v[144:147], v[180:183], v[68:71]
	s_barrier
	v_cndmask_b32_e64 v0, 0, 1, s[30:31]
	v_cmp_ne_u32_e64 s[6:7], 1, v0
	s_andn2_b64 vcc, exec, s[30:31]
	s_cbranch_vccnz .LBB0_449
	ds_read_b128 v[176:179], v241 offset:16384
	ds_read_b128 v[192:195], v241 offset:17408
	ds_read_b128 v[172:175], v241 offset:18432
	ds_read_b128 v[188:191], v241 offset:19456
	ds_read_b128 v[168:171], v241 offset:20480
	ds_read_b128 v[184:187], v241 offset:21504
	ds_read_b128 v[164:167], v241 offset:22528
	ds_read_b128 v[180:183], v241 offset:23552
.LBB0_449:
	s_add_u32 s34, s24, s28
	s_addc_u32 s35, s25, s29
	s_add_u32 s36, s34, 0x100
	s_addc_u32 s37, s35, 0
	s_add_u32 s88, s0, s28
	s_addc_u32 s89, s72, s29
	s_cmpk_eq_i32 s28, 0xf00
	s_cselect_b64 s[38:39], -1, 0
	s_and_b64 s[34:35], s[38:39], exec
	s_cselect_b32 s35, s13, s89
	s_cselect_b32 s34, s94, s88
	s_mov_b32 m0, s43
	s_cselect_b32 s37, s15, s37
	s_cselect_b32 s36, s81, s36
	v_lshl_add_u64 v[2:3], s[34:35], 0, v[204:205]
	s_add_u32 s88, s34, 0x80000
	global_load_lds_dwordx4 v[2:3], off
	v_lshl_add_u64 v[218:219], s[34:35], 0, v[208:209]
	s_mov_b32 m0, s49
	s_addc_u32 s89, s35, 0
	global_load_lds_dwordx4 v[218:219], off
	v_lshl_add_u64 v[220:221], s[88:89], 0, v[204:205]
	s_mov_b32 m0, s51
	v_lshl_add_u64 v[222:223], s[36:37], 0, v[206:207]
	global_load_lds_dwordx4 v[220:221], off
	v_lshl_add_u64 v[220:221], s[88:89], 0, v[208:209]
	s_mov_b32 m0, s52
	s_and_b64 vcc, exec, s[6:7]
	global_load_lds_dwordx4 v[220:221], off
	v_lshl_add_u64 v[220:221], s[36:37], 0, v[202:203]
	s_mov_b32 m0, s53
	s_nop 0
	global_load_lds_dwordx4 v[220:221], off
	s_mov_b32 m0, s54
	s_nop 0
	global_load_lds_dwordx4 v[222:223], off
	s_waitcnt vmcnt(8)
	s_waitcnt lgkmcnt(0)
	s_barrier
	s_cbranch_vccnz .LBB0_451
	s_waitcnt lgkmcnt(0)
	v_mfma_f32_16x16x32_bf16 v[64:67], v[148:151], v[176:179], v[64:67]
	v_mfma_f32_16x16x32_bf16 v[56:59], v[156:159], v[176:179], v[56:59]
	v_mfma_f32_16x16x32_bf16 v[48:51], v[148:151], v[172:175], v[48:51]
	v_mfma_f32_16x16x32_bf16 v[40:43], v[156:159], v[172:175], v[40:43]
	v_mfma_f32_16x16x32_bf16 v[32:35], v[148:151], v[168:171], v[32:35]
	v_mfma_f32_16x16x32_bf16 v[24:27], v[156:159], v[168:171], v[24:27]
	v_mfma_f32_16x16x32_bf16 v[16:19], v[148:151], v[164:167], v[16:19]
	v_mfma_f32_16x16x32_bf16 v[8:11], v[156:159], v[164:167], v[8:11]
	v_mfma_f32_16x16x32_bf16 v[64:67], v[152:155], v[192:195], v[64:67]
	v_mfma_f32_16x16x32_bf16 v[56:59], v[160:163], v[192:195], v[56:59]
	v_mfma_f32_16x16x32_bf16 v[48:51], v[152:155], v[188:191], v[48:51]
	v_mfma_f32_16x16x32_bf16 v[40:43], v[160:163], v[188:191], v[40:43]
	v_mfma_f32_16x16x32_bf16 v[32:35], v[152:155], v[184:187], v[32:35]
	v_mfma_f32_16x16x32_bf16 v[24:27], v[160:163], v[184:187], v[24:27]
	v_mfma_f32_16x16x32_bf16 v[16:19], v[152:155], v[180:183], v[16:19]
	v_mfma_f32_16x16x32_bf16 v[8:11], v[160:163], v[180:183], v[8:11]
	v_mfma_f32_16x16x32_bf16 v[60:63], v[132:135], v[176:179], v[60:63]
	v_mfma_f32_16x16x32_bf16 v[52:55], v[140:143], v[176:179], v[52:55]
	v_mfma_f32_16x16x32_bf16 v[44:47], v[132:135], v[172:175], v[44:47]
	v_mfma_f32_16x16x32_bf16 v[36:39], v[140:143], v[172:175], v[36:39]
	v_mfma_f32_16x16x32_bf16 v[28:31], v[132:135], v[168:171], v[28:31]
	v_mfma_f32_16x16x32_bf16 v[20:23], v[140:143], v[168:171], v[20:23]
	v_mfma_f32_16x16x32_bf16 v[12:15], v[132:135], v[164:167], v[12:15]
	v_mfma_f32_16x16x32_bf16 v[4:7], v[140:143], v[164:167], v[4:7]
	v_mfma_f32_16x16x32_bf16 v[60:63], v[136:139], v[192:195], v[60:63]
	v_mfma_f32_16x16x32_bf16 v[52:55], v[144:147], v[192:195], v[52:55]
	v_mfma_f32_16x16x32_bf16 v[44:47], v[136:139], v[188:191], v[44:47]
	v_mfma_f32_16x16x32_bf16 v[36:39], v[144:147], v[188:191], v[36:39]
	v_mfma_f32_16x16x32_bf16 v[28:31], v[136:139], v[184:187], v[28:31]
	v_mfma_f32_16x16x32_bf16 v[20:23], v[144:147], v[184:187], v[20:23]
	v_mfma_f32_16x16x32_bf16 v[12:15], v[136:139], v[180:183], v[12:15]
	v_mfma_f32_16x16x32_bf16 v[4:7], v[144:147], v[180:183], v[4:7]
.LBB0_451:
	s_barrier
	v_add_u32_e32 v0, s57, v225
	ds_read_b128 v[148:151], v0
	ds_read_b128 v[152:155], v0 offset:1024
	ds_read_b128 v[156:159], v0 offset:2048
	ds_read_b128 v[160:163], v0 offset:3072
	v_add_u32_e32 v0, s66, v225
	ds_read_b128 v[132:135], v0
	ds_read_b128 v[136:139], v0 offset:1024
	ds_read_b128 v[140:143], v0 offset:2048
	ds_read_b128 v[144:147], v0 offset:3072
	s_and_b64 s[38:39], s[16:17], s[38:39]
	s_and_b64 s[38:39], s[38:39], exec
	s_cselect_b32 s39, s74, s26
	s_cselect_b32 s38, 0, s27
	s_add_u32 s36, s36, s39
	s_addc_u32 s37, s37, s38
	s_mov_b32 m0, s55
	v_lshl_add_u64 v[242:243], s[36:37], 0, v[202:203]
	s_waitcnt lgkmcnt(0)
	ds_read_b128 v[176:179], v241 offset:32768
	ds_read_b128 v[192:195], v241 offset:33792
	ds_read_b128 v[172:175], v241 offset:34816
	ds_read_b128 v[188:191], v241 offset:35840
	ds_read_b128 v[168:171], v241 offset:36864
	ds_read_b128 v[184:187], v241 offset:37888
	ds_read_b128 v[164:167], v241 offset:38912
	ds_read_b128 v[180:183], v241 offset:39936
	global_load_lds_dwordx4 v[242:243], off
	v_lshl_add_u64 v[242:243], s[36:37], 0, v[206:207]
	s_mov_b32 m0, s56
	s_nop 0
	global_load_lds_dwordx4 v[242:243], off
	s_waitcnt vmcnt(8)
	s_waitcnt lgkmcnt(0)
	s_barrier
	s_waitcnt lgkmcnt(0)
	v_mfma_f32_16x16x32_bf16 v[128:131], v[148:151], v[176:179], v[128:131]
	v_mfma_f32_16x16x32_bf16 v[120:123], v[156:159], v[176:179], v[120:123]
	v_mfma_f32_16x16x32_bf16 v[112:115], v[148:151], v[172:175], v[112:115]
	v_mfma_f32_16x16x32_bf16 v[104:107], v[156:159], v[172:175], v[104:107]
	v_mfma_f32_16x16x32_bf16 v[96:99], v[148:151], v[168:171], v[96:99]
	v_mfma_f32_16x16x32_bf16 v[88:91], v[156:159], v[168:171], v[88:91]
	v_mfma_f32_16x16x32_bf16 v[80:83], v[148:151], v[164:167], v[80:83]
	v_mfma_f32_16x16x32_bf16 v[72:75], v[156:159], v[164:167], v[72:75]
	v_mfma_f32_16x16x32_bf16 v[128:131], v[152:155], v[192:195], v[128:131]
	v_mfma_f32_16x16x32_bf16 v[120:123], v[160:163], v[192:195], v[120:123]
	v_mfma_f32_16x16x32_bf16 v[112:115], v[152:155], v[188:191], v[112:115]
	v_mfma_f32_16x16x32_bf16 v[104:107], v[160:163], v[188:191], v[104:107]
	v_mfma_f32_16x16x32_bf16 v[96:99], v[152:155], v[184:187], v[96:99]
	v_mfma_f32_16x16x32_bf16 v[88:91], v[160:163], v[184:187], v[88:91]
	v_mfma_f32_16x16x32_bf16 v[80:83], v[152:155], v[180:183], v[80:83]
	v_mfma_f32_16x16x32_bf16 v[72:75], v[160:163], v[180:183], v[72:75]
	v_mfma_f32_16x16x32_bf16 v[124:127], v[132:135], v[176:179], v[124:127]
	v_mfma_f32_16x16x32_bf16 v[116:119], v[140:143], v[176:179], v[116:119]
	v_mfma_f32_16x16x32_bf16 v[108:111], v[132:135], v[172:175], v[108:111]
	v_mfma_f32_16x16x32_bf16 v[100:103], v[140:143], v[172:175], v[100:103]
	v_mfma_f32_16x16x32_bf16 v[92:95], v[132:135], v[168:171], v[92:95]
	v_mfma_f32_16x16x32_bf16 v[84:87], v[140:143], v[168:171], v[84:87]
	v_mfma_f32_16x16x32_bf16 v[76:79], v[132:135], v[164:167], v[76:79]
	v_mfma_f32_16x16x32_bf16 v[68:71], v[140:143], v[164:167], v[68:71]
	v_mfma_f32_16x16x32_bf16 v[124:127], v[136:139], v[192:195], v[124:127]
	v_mfma_f32_16x16x32_bf16 v[116:119], v[144:147], v[192:195], v[116:119]
	v_mfma_f32_16x16x32_bf16 v[108:111], v[136:139], v[188:191], v[108:111]
	v_mfma_f32_16x16x32_bf16 v[100:103], v[144:147], v[188:191], v[100:103]
	v_mfma_f32_16x16x32_bf16 v[92:95], v[136:139], v[184:187], v[92:95]
	v_mfma_f32_16x16x32_bf16 v[84:87], v[144:147], v[184:187], v[84:87]
	v_mfma_f32_16x16x32_bf16 v[76:79], v[136:139], v[180:183], v[76:79]
	v_mfma_f32_16x16x32_bf16 v[68:71], v[144:147], v[180:183], v[68:71]
	s_barrier
	s_and_b64 vcc, exec, s[6:7]
	s_mov_b64 s[88:89], s[86:87]
	s_cbranch_vccnz .LBB0_453
	ds_read_b128 v[176:179], v241 offset:49152
	ds_read_b128 v[192:195], v241 offset:50176
	ds_read_b128 v[172:175], v241 offset:51200
	ds_read_b128 v[188:191], v241 offset:52224
	ds_read_b128 v[168:171], v241 offset:53248
	ds_read_b128 v[184:187], v241 offset:54272
	ds_read_b128 v[164:167], v241 offset:55296
	ds_read_b128 v[180:183], v241 offset:56320
.LBB0_453:
	s_mov_b32 m0, s58
	v_lshl_add_u64 v[2:3], v[2:3], 0, s[44:45]
	s_add_u32 s34, s34, 0x80080
	global_load_lds_dwordx4 v[2:3], off
	v_lshl_add_u64 v[2:3], v[218:219], 0, s[44:45]
	s_mov_b32 m0, s59
	s_addc_u32 s35, s35, 0
	global_load_lds_dwordx4 v[2:3], off
	v_lshl_add_u64 v[2:3], s[34:35], 0, v[204:205]
	s_mov_b32 m0, s67
	s_and_b64 vcc, exec, s[6:7]
	global_load_lds_dwordx4 v[2:3], off
	v_lshl_add_u64 v[2:3], s[34:35], 0, v[208:209]
	s_mov_b32 m0, s70
	s_nop 0
	global_load_lds_dwordx4 v[2:3], off
	v_lshl_add_u64 v[2:3], v[220:221], 0, s[44:45]
	s_mov_b32 m0, s60
	s_nop 0
	global_load_lds_dwordx4 v[2:3], off
	v_lshl_add_u64 v[2:3], v[222:223], 0, s[44:45]
	s_mov_b32 m0, s61
	s_nop 0
	global_load_lds_dwordx4 v[2:3], off
	s_waitcnt vmcnt(8)
	s_waitcnt lgkmcnt(0)
	s_barrier
	s_cbranch_vccnz .LBB0_446
	s_waitcnt lgkmcnt(0)
	v_mfma_f32_16x16x32_bf16 v[64:67], v[148:151], v[176:179], v[64:67]
	v_mfma_f32_16x16x32_bf16 v[56:59], v[156:159], v[176:179], v[56:59]
	v_mfma_f32_16x16x32_bf16 v[48:51], v[148:151], v[172:175], v[48:51]
	v_mfma_f32_16x16x32_bf16 v[40:43], v[156:159], v[172:175], v[40:43]
	v_mfma_f32_16x16x32_bf16 v[32:35], v[148:151], v[168:171], v[32:35]
	v_mfma_f32_16x16x32_bf16 v[24:27], v[156:159], v[168:171], v[24:27]
	v_mfma_f32_16x16x32_bf16 v[16:19], v[148:151], v[164:167], v[16:19]
	v_mfma_f32_16x16x32_bf16 v[8:11], v[156:159], v[164:167], v[8:11]
	v_mfma_f32_16x16x32_bf16 v[64:67], v[152:155], v[192:195], v[64:67]
	v_mfma_f32_16x16x32_bf16 v[56:59], v[160:163], v[192:195], v[56:59]
	v_mfma_f32_16x16x32_bf16 v[48:51], v[152:155], v[188:191], v[48:51]
	v_mfma_f32_16x16x32_bf16 v[40:43], v[160:163], v[188:191], v[40:43]
	v_mfma_f32_16x16x32_bf16 v[32:35], v[152:155], v[184:187], v[32:35]
	v_mfma_f32_16x16x32_bf16 v[24:27], v[160:163], v[184:187], v[24:27]
	v_mfma_f32_16x16x32_bf16 v[16:19], v[152:155], v[180:183], v[16:19]
	v_mfma_f32_16x16x32_bf16 v[8:11], v[160:163], v[180:183], v[8:11]
	v_mfma_f32_16x16x32_bf16 v[60:63], v[132:135], v[176:179], v[60:63]
	v_mfma_f32_16x16x32_bf16 v[52:55], v[140:143], v[176:179], v[52:55]
	v_mfma_f32_16x16x32_bf16 v[44:47], v[132:135], v[172:175], v[44:47]
	v_mfma_f32_16x16x32_bf16 v[36:39], v[140:143], v[172:175], v[36:39]
	v_mfma_f32_16x16x32_bf16 v[28:31], v[132:135], v[168:171], v[28:31]
	v_mfma_f32_16x16x32_bf16 v[20:23], v[140:143], v[168:171], v[20:23]
	v_mfma_f32_16x16x32_bf16 v[12:15], v[132:135], v[164:167], v[12:15]
	v_mfma_f32_16x16x32_bf16 v[2:5], v[140:143], v[164:167], v[4:7]
	v_mfma_f32_16x16x32_bf16 v[60:63], v[136:139], v[192:195], v[60:63]
	v_mfma_f32_16x16x32_bf16 v[52:55], v[144:147], v[192:195], v[52:55]
	v_mfma_f32_16x16x32_bf16 v[44:47], v[136:139], v[188:191], v[44:47]
	v_mfma_f32_16x16x32_bf16 v[36:39], v[144:147], v[188:191], v[36:39]
	v_mfma_f32_16x16x32_bf16 v[28:31], v[136:139], v[184:187], v[28:31]
	v_mfma_f32_16x16x32_bf16 v[20:23], v[144:147], v[184:187], v[20:23]
	v_mfma_f32_16x16x32_bf16 v[12:15], v[136:139], v[180:183], v[12:15]
	v_mfma_f32_16x16x32_bf16 v[4:7], v[144:147], v[180:183], v[2:5]
	s_branch .LBB0_446

.LBB0_629:
	v_add_u32_e32 v110, s29, v159
	v_add_u32_e32 v126, s34, v159
	ds_read_b128 v[98:101], v110
	ds_read_b128 v[102:105], v110 offset:1024
	ds_read_b128 v[106:109], v110 offset:2048
	ds_read_b128 v[110:113], v110 offset:3072
	ds_read_b128 v[114:117], v126
	ds_read_b128 v[118:121], v126 offset:1024
	ds_read_b128 v[122:125], v126 offset:2048
	ds_read_b128 v[126:129], v126 offset:3072
	s_add_u32 s8, s10, 0x100
	s_addc_u32 s9, s11, 0
	s_cmpk_eq_i32 s67, 0x54
	s_cselect_b32 s71, s21, s9
	s_cselect_b32 s70, s20, s8
	s_cselect_b32 s25, s23, s66
	s_cselect_b32 s24, s22, s0
	v_lshl_add_u64 v[172:173], s[10:11], 0, v[132:133]
	s_add_i32 m0, s37, 0xc000
	ds_read_b128 v[134:137], v162
	ds_read_b128 v[138:141], v162 offset:1024
	ds_read_b128 v[142:145], v162 offset:2048
	ds_read_b128 v[146:149], v162 offset:3072
	ds_read_b128 v[150:153], v162 offset:4096
	ds_read_b128 v[154:157], v162 offset:5120
	ds_read_b128 v[164:167], v162 offset:6144
	ds_read_b128 v[168:171], v162 offset:7168
	global_load_lds_dwordx4 v[172:173], off
	s_waitcnt vmcnt(7)
	s_waitcnt lgkmcnt(0)
	s_barrier
	s_waitcnt lgkmcnt(0)
	v_mfma_f32_16x16x32_bf16 v[94:97], v[98:101], v[134:137], v[94:97]
	v_mfma_f32_16x16x32_bf16 v[90:93], v[106:109], v[134:137], v[90:93]
	v_mfma_f32_16x16x32_bf16 v[78:81], v[98:101], v[142:145], v[78:81]
	v_mfma_f32_16x16x32_bf16 v[74:77], v[106:109], v[142:145], v[74:77]
	v_mfma_f32_16x16x32_bf16 v[62:65], v[98:101], v[150:153], v[62:65]
	v_mfma_f32_16x16x32_bf16 v[58:61], v[106:109], v[150:153], v[58:61]
	v_mfma_f32_16x16x32_bf16 v[46:49], v[98:101], v[164:167], v[46:49]
	v_mfma_f32_16x16x32_bf16 v[42:45], v[106:109], v[164:167], v[42:45]
	v_mfma_f32_16x16x32_bf16 v[94:97], v[102:105], v[138:141], v[94:97]
	v_mfma_f32_16x16x32_bf16 v[90:93], v[110:113], v[138:141], v[90:93]
	v_mfma_f32_16x16x32_bf16 v[78:81], v[102:105], v[146:149], v[78:81]
	v_mfma_f32_16x16x32_bf16 v[74:77], v[110:113], v[146:149], v[74:77]
	v_mfma_f32_16x16x32_bf16 v[62:65], v[102:105], v[154:157], v[62:65]
	v_mfma_f32_16x16x32_bf16 v[58:61], v[110:113], v[154:157], v[58:61]
	v_mfma_f32_16x16x32_bf16 v[46:49], v[102:105], v[168:171], v[46:49]
	v_mfma_f32_16x16x32_bf16 v[42:45], v[110:113], v[168:171], v[42:45]
	v_mfma_f32_16x16x32_bf16 v[86:89], v[114:117], v[134:137], v[86:89]
	v_mfma_f32_16x16x32_bf16 v[82:85], v[122:125], v[134:137], v[82:85]
	v_mfma_f32_16x16x32_bf16 v[70:73], v[114:117], v[142:145], v[70:73]
	v_mfma_f32_16x16x32_bf16 v[66:69], v[122:125], v[142:145], v[66:69]
	v_mfma_f32_16x16x32_bf16 v[54:57], v[114:117], v[150:153], v[54:57]
	v_mfma_f32_16x16x32_bf16 v[50:53], v[122:125], v[150:153], v[50:53]
	v_mfma_f32_16x16x32_bf16 v[38:41], v[114:117], v[164:167], v[38:41]
	v_mfma_f32_16x16x32_bf16 v[34:37], v[122:125], v[164:167], v[34:37]
	v_mfma_f32_16x16x32_bf16 v[86:89], v[118:121], v[138:141], v[86:89]
	v_mfma_f32_16x16x32_bf16 v[82:85], v[126:129], v[138:141], v[82:85]
	v_mfma_f32_16x16x32_bf16 v[70:73], v[118:121], v[146:149], v[70:73]
	v_mfma_f32_16x16x32_bf16 v[66:69], v[126:129], v[146:149], v[66:69]
	v_mfma_f32_16x16x32_bf16 v[54:57], v[118:121], v[154:157], v[54:57]
	v_mfma_f32_16x16x32_bf16 v[50:53], v[126:129], v[154:157], v[50:53]
	v_mfma_f32_16x16x32_bf16 v[38:41], v[118:121], v[168:171], v[38:41]
	v_mfma_f32_16x16x32_bf16 v[34:37], v[126:129], v[168:171], v[34:37]
	s_barrier
	s_mov_b32 m0, s30
	v_lshl_add_u64 v[172:173], s[24:25], 0, v[0:1]
	s_add_u32 s10, s24, 0x160000
	ds_read_b128 v[134:137], v163 offset:16384
	ds_read_b128 v[138:141], v163 offset:17408
	ds_read_b128 v[142:145], v163 offset:18432
	ds_read_b128 v[146:149], v163 offset:19456
	global_load_lds_dwordx4 v[172:173], off
	v_lshl_add_u64 v[174:175], s[24:25], 0, v[130:131]
	s_mov_b32 m0, s31
	s_addc_u32 s11, s25, 0
	global_load_lds_dwordx4 v[174:175], off
	v_lshl_add_u64 v[150:151], s[10:11], 0, v[0:1]
	s_mov_b32 m0, s35
	v_lshl_add_u64 v[176:177], s[70:71], 0, v[0:1]
	global_load_lds_dwordx4 v[150:151], off
	v_lshl_add_u64 v[150:151], s[10:11], 0, v[130:131]
	s_mov_b32 m0, s36
	v_lshl_add_u64 v[178:179], s[70:71], 0, v[130:131]
	global_load_lds_dwordx4 v[150:151], off
	s_mov_b32 m0, s37
	s_nop 0
	global_load_lds_dwordx4 v[176:177], off
	s_mov_b32 m0, s38
	s_nop 0
	global_load_lds_dwordx4 v[178:179], off
	s_waitcnt vmcnt(7)
	s_waitcnt lgkmcnt(0)
	s_barrier
	s_waitcnt lgkmcnt(0)
	v_mfma_f32_16x16x32_bf16 v[30:33], v[98:101], v[134:137], v[30:33]
	v_mfma_f32_16x16x32_bf16 v[26:29], v[106:109], v[134:137], v[26:29]
	v_mfma_f32_16x16x32_bf16 v[14:17], v[98:101], v[142:145], v[14:17]
	v_mfma_f32_16x16x32_bf16 v[10:13], v[106:109], v[142:145], v[10:13]
	v_mfma_f32_16x16x32_bf16 v[30:33], v[102:105], v[138:141], v[30:33]
	v_mfma_f32_16x16x32_bf16 v[26:29], v[110:113], v[138:141], v[26:29]
	v_mfma_f32_16x16x32_bf16 v[14:17], v[102:105], v[146:149], v[14:17]
	v_mfma_f32_16x16x32_bf16 v[10:13], v[110:113], v[146:149], v[10:13]
	v_mfma_f32_16x16x32_bf16 v[22:25], v[114:117], v[134:137], v[22:25]
	v_mfma_f32_16x16x32_bf16 v[18:21], v[122:125], v[134:137], v[18:21]
	v_mfma_f32_16x16x32_bf16 v[6:9], v[114:117], v[142:145], v[6:9]
	v_mfma_f32_16x16x32_bf16 v[2:5], v[122:125], v[142:145], v[2:5]
	v_mfma_f32_16x16x32_bf16 v[22:25], v[118:121], v[138:141], v[22:25]
	v_mfma_f32_16x16x32_bf16 v[18:21], v[126:129], v[138:141], v[18:21]
	v_mfma_f32_16x16x32_bf16 v[6:9], v[118:121], v[146:149], v[6:9]
	v_mfma_f32_16x16x32_bf16 v[2:5], v[126:129], v[146:149], v[2:5]
	s_barrier
	v_add_u32_e32 v110, s43, v159
	v_add_u32_e32 v126, s53, v159
	ds_read_b128 v[98:101], v110
	ds_read_b128 v[102:105], v110 offset:1024
	ds_read_b128 v[106:109], v110 offset:2048
	ds_read_b128 v[110:113], v110 offset:3072
	ds_read_b128 v[114:117], v126
	ds_read_b128 v[118:121], v126 offset:1024
	ds_read_b128 v[122:125], v126 offset:2048
	ds_read_b128 v[126:129], v126 offset:3072
	v_lshl_add_u64 v[180:181], v[176:177], 0, s[82:83]
	s_mov_b32 m0, s39
	ds_read_b128 v[134:137], v162 offset:32768
	ds_read_b128 v[138:141], v162 offset:33792
	ds_read_b128 v[142:145], v162 offset:34816
	ds_read_b128 v[146:149], v162 offset:35840
	ds_read_b128 v[150:153], v162 offset:36864
	ds_read_b128 v[154:157], v162 offset:37888
	ds_read_b128 v[164:167], v162 offset:38912
	ds_read_b128 v[168:171], v162 offset:39936
	global_load_lds_dwordx4 v[180:181], off
	s_waitcnt vmcnt(7)
	s_waitcnt lgkmcnt(0)
	s_barrier
	s_waitcnt lgkmcnt(0)
	v_mfma_f32_16x16x32_bf16 v[94:97], v[98:101], v[134:137], v[94:97]
	v_mfma_f32_16x16x32_bf16 v[90:93], v[106:109], v[134:137], v[90:93]
	v_mfma_f32_16x16x32_bf16 v[78:81], v[98:101], v[142:145], v[78:81]
	v_mfma_f32_16x16x32_bf16 v[74:77], v[106:109], v[142:145], v[74:77]
	v_mfma_f32_16x16x32_bf16 v[62:65], v[98:101], v[150:153], v[62:65]
	v_mfma_f32_16x16x32_bf16 v[58:61], v[106:109], v[150:153], v[58:61]
	v_mfma_f32_16x16x32_bf16 v[46:49], v[98:101], v[164:167], v[46:49]
	v_mfma_f32_16x16x32_bf16 v[42:45], v[106:109], v[164:167], v[42:45]
	v_mfma_f32_16x16x32_bf16 v[94:97], v[102:105], v[138:141], v[94:97]
	v_mfma_f32_16x16x32_bf16 v[90:93], v[110:113], v[138:141], v[90:93]
	v_mfma_f32_16x16x32_bf16 v[78:81], v[102:105], v[146:149], v[78:81]
	v_mfma_f32_16x16x32_bf16 v[74:77], v[110:113], v[146:149], v[74:77]
	v_mfma_f32_16x16x32_bf16 v[62:65], v[102:105], v[154:157], v[62:65]
	v_mfma_f32_16x16x32_bf16 v[58:61], v[110:113], v[154:157], v[58:61]
	v_mfma_f32_16x16x32_bf16 v[46:49], v[102:105], v[168:171], v[46:49]
	v_mfma_f32_16x16x32_bf16 v[42:45], v[110:113], v[168:171], v[42:45]
	v_mfma_f32_16x16x32_bf16 v[86:89], v[114:117], v[134:137], v[86:89]
	v_mfma_f32_16x16x32_bf16 v[82:85], v[122:125], v[134:137], v[82:85]
	v_mfma_f32_16x16x32_bf16 v[70:73], v[114:117], v[142:145], v[70:73]
	v_mfma_f32_16x16x32_bf16 v[66:69], v[122:125], v[142:145], v[66:69]
	v_mfma_f32_16x16x32_bf16 v[54:57], v[114:117], v[150:153], v[54:57]
	v_mfma_f32_16x16x32_bf16 v[50:53], v[122:125], v[150:153], v[50:53]
	v_mfma_f32_16x16x32_bf16 v[38:41], v[114:117], v[164:167], v[38:41]
	v_mfma_f32_16x16x32_bf16 v[34:37], v[122:125], v[164:167], v[34:37]
	v_mfma_f32_16x16x32_bf16 v[86:89], v[118:121], v[138:141], v[86:89]
	v_mfma_f32_16x16x32_bf16 v[82:85], v[126:129], v[138:141], v[82:85]
	v_mfma_f32_16x16x32_bf16 v[70:73], v[118:121], v[146:149], v[70:73]
	v_mfma_f32_16x16x32_bf16 v[66:69], v[126:129], v[146:149], v[66:69]
	v_mfma_f32_16x16x32_bf16 v[54:57], v[118:121], v[154:157], v[54:57]
	v_mfma_f32_16x16x32_bf16 v[50:53], v[126:129], v[154:157], v[50:53]
	v_mfma_f32_16x16x32_bf16 v[38:41], v[118:121], v[168:171], v[38:41]
	v_mfma_f32_16x16x32_bf16 v[34:37], v[126:129], v[168:171], v[34:37]
	s_barrier
	s_mov_b32 m0, s49
	v_lshl_add_u64 v[150:151], v[172:173], 0, s[44:45]
	s_add_u32 s10, s24, 0x160080
	ds_read_b128 v[134:137], v163 offset:49152
	ds_read_b128 v[138:141], v163 offset:50176
	ds_read_b128 v[142:145], v163 offset:51200
	ds_read_b128 v[146:149], v163 offset:52224
	global_load_lds_dwordx4 v[150:151], off
	v_lshl_add_u64 v[150:151], v[174:175], 0, s[44:45]
	s_mov_b32 m0, s50
	s_addc_u32 s11, s25, 0
	global_load_lds_dwordx4 v[150:151], off
	v_lshl_add_u64 v[150:151], s[10:11], 0, v[0:1]
	s_mov_b32 m0, s54
	s_nop 0
	global_load_lds_dwordx4 v[150:151], off
	v_lshl_add_u64 v[150:151], s[10:11], 0, v[130:131]
	s_mov_b32 m0, s55
	s_nop 0
	global_load_lds_dwordx4 v[150:151], off
	v_lshl_add_u64 v[150:151], v[176:177], 0, s[44:45]
	s_mov_b32 m0, s51
	s_nop 0
	global_load_lds_dwordx4 v[150:151], off
	v_lshl_add_u64 v[150:151], v[178:179], 0, s[44:45]
	s_mov_b32 m0, s52
	s_nop 0
	global_load_lds_dwordx4 v[150:151], off
	s_waitcnt vmcnt(7)
	s_waitcnt lgkmcnt(0)
	s_barrier
	s_waitcnt lgkmcnt(0)
	v_mfma_f32_16x16x32_bf16 v[30:33], v[98:101], v[134:137], v[30:33]
	v_mfma_f32_16x16x32_bf16 v[26:29], v[106:109], v[134:137], v[26:29]
	v_mfma_f32_16x16x32_bf16 v[14:17], v[98:101], v[142:145], v[14:17]
	v_mfma_f32_16x16x32_bf16 v[10:13], v[106:109], v[142:145], v[10:13]
	v_mfma_f32_16x16x32_bf16 v[30:33], v[102:105], v[138:141], v[30:33]
	v_mfma_f32_16x16x32_bf16 v[26:29], v[110:113], v[138:141], v[26:29]
	v_mfma_f32_16x16x32_bf16 v[14:17], v[102:105], v[146:149], v[14:17]
	v_mfma_f32_16x16x32_bf16 v[10:13], v[110:113], v[146:149], v[10:13]
	v_mfma_f32_16x16x32_bf16 v[22:25], v[114:117], v[134:137], v[22:25]
	v_mfma_f32_16x16x32_bf16 v[18:21], v[122:125], v[134:137], v[18:21]
	v_mfma_f32_16x16x32_bf16 v[6:9], v[114:117], v[142:145], v[6:9]
	v_mfma_f32_16x16x32_bf16 v[2:5], v[122:125], v[142:145], v[2:5]
	v_mfma_f32_16x16x32_bf16 v[22:25], v[118:121], v[138:141], v[22:25]
	v_mfma_f32_16x16x32_bf16 v[18:21], v[126:129], v[138:141], v[18:21]
	v_mfma_f32_16x16x32_bf16 v[6:9], v[118:121], v[146:149], v[6:9]
	v_mfma_f32_16x16x32_bf16 v[2:5], v[126:129], v[146:149], v[2:5]
	s_barrier
	s_add_i32 s67, s67, 2
	s_add_u32 s0, s0, 0x100
	s_addc_u32 s66, s66, 0
	s_cmpk_gt_u32 s67, 0x55
	s_mov_b64 s[10:11], s[8:9]
	s_cbranch_scc0 .LBB0_629
	s_and_b64 vcc, exec, s[18:19]
	s_cbranch_vccz .LBB0_632
	s_barrier

.LBB0_773:
	v_add_u32_e32 v0, s15, v241
	ds_read_b128 v[148:151], v0
	ds_read_b128 v[152:155], v0 offset:1024
	ds_read_b128 v[156:159], v0 offset:2048
	ds_read_b128 v[160:163], v0 offset:3072
	v_add_u32_e32 v0, s54, v241
	ds_read_b128 v[132:135], v0
	ds_read_b128 v[136:139], v0 offset:1024
	ds_read_b128 v[140:143], v0 offset:2048
	ds_read_b128 v[144:147], v0 offset:3072
	v_lshl_add_u64 v[2:3], v[218:219], 0, s[34:35]
	s_add_i32 m0, s57, 0xc000
	s_waitcnt lgkmcnt(0)
	ds_read_b128 v[176:179], v243
	ds_read_b128 v[192:195], v243 offset:1024
	ds_read_b128 v[172:175], v243 offset:2048
	ds_read_b128 v[188:191], v243 offset:3072
	ds_read_b128 v[168:171], v243 offset:4096
	ds_read_b128 v[184:187], v243 offset:5120
	ds_read_b128 v[164:167], v243 offset:6144
	ds_read_b128 v[180:183], v243 offset:7168
	global_load_lds_dwordx4 v[2:3], off
	v_lshl_add_u64 v[2:3], v[216:217], 0, s[34:35]
	s_add_i32 m0, s57, 0xe000
	s_nop 0
	global_load_lds_dwordx4 v[2:3], off
	s_waitcnt vmcnt(8)
	s_waitcnt lgkmcnt(0)
	s_barrier
	s_waitcnt lgkmcnt(0)
	v_mfma_f32_16x16x32_bf16 v[128:131], v[148:151], v[176:179], v[128:131]
	v_mfma_f32_16x16x32_bf16 v[124:127], v[156:159], v[176:179], v[124:127]
	v_mfma_f32_16x16x32_bf16 v[120:123], v[148:151], v[172:175], v[120:123]
	v_mfma_f32_16x16x32_bf16 v[112:115], v[156:159], v[172:175], v[112:115]
	v_mfma_f32_16x16x32_bf16 v[104:107], v[148:151], v[168:171], v[104:107]
	v_mfma_f32_16x16x32_bf16 v[96:99], v[156:159], v[168:171], v[96:99]
	v_mfma_f32_16x16x32_bf16 v[88:91], v[148:151], v[164:167], v[88:91]
	v_mfma_f32_16x16x32_bf16 v[80:83], v[156:159], v[164:167], v[80:83]
	v_mfma_f32_16x16x32_bf16 v[128:131], v[152:155], v[192:195], v[128:131]
	v_mfma_f32_16x16x32_bf16 v[124:127], v[160:163], v[192:195], v[124:127]
	v_mfma_f32_16x16x32_bf16 v[120:123], v[152:155], v[188:191], v[120:123]
	v_mfma_f32_16x16x32_bf16 v[112:115], v[160:163], v[188:191], v[112:115]
	v_mfma_f32_16x16x32_bf16 v[104:107], v[152:155], v[184:187], v[104:107]
	v_mfma_f32_16x16x32_bf16 v[96:99], v[160:163], v[184:187], v[96:99]
	v_mfma_f32_16x16x32_bf16 v[88:91], v[152:155], v[180:183], v[88:91]
	v_mfma_f32_16x16x32_bf16 v[80:83], v[160:163], v[180:183], v[80:83]
	v_mfma_f32_16x16x32_bf16 v[116:119], v[132:135], v[176:179], v[116:119]
	v_mfma_f32_16x16x32_bf16 v[108:111], v[140:143], v[176:179], v[108:111]
	v_mfma_f32_16x16x32_bf16 v[100:103], v[132:135], v[172:175], v[100:103]
	v_mfma_f32_16x16x32_bf16 v[92:95], v[140:143], v[172:175], v[92:95]
	v_mfma_f32_16x16x32_bf16 v[84:87], v[132:135], v[168:171], v[84:87]
	v_mfma_f32_16x16x32_bf16 v[76:79], v[140:143], v[168:171], v[76:79]
	v_mfma_f32_16x16x32_bf16 v[72:75], v[132:135], v[164:167], v[72:75]
	v_mfma_f32_16x16x32_bf16 v[68:71], v[140:143], v[164:167], v[68:71]
	v_mfma_f32_16x16x32_bf16 v[116:119], v[136:139], v[192:195], v[116:119]
	v_mfma_f32_16x16x32_bf16 v[108:111], v[144:147], v[192:195], v[108:111]
	v_mfma_f32_16x16x32_bf16 v[100:103], v[136:139], v[188:191], v[100:103]
	v_mfma_f32_16x16x32_bf16 v[92:95], v[144:147], v[188:191], v[92:95]
	v_mfma_f32_16x16x32_bf16 v[84:87], v[136:139], v[184:187], v[84:87]
	v_mfma_f32_16x16x32_bf16 v[76:79], v[144:147], v[184:187], v[76:79]
	v_mfma_f32_16x16x32_bf16 v[72:75], v[136:139], v[180:183], v[72:75]
	v_mfma_f32_16x16x32_bf16 v[68:71], v[144:147], v[180:183], v[68:71]
	s_barrier
	v_cndmask_b32_e64 v0, 0, 1, s[36:37]
	v_cmp_ne_u32_e64 s[6:7], 1, v0
	s_andn2_b64 vcc, exec, s[36:37]
	s_cbranch_vccnz .LBB0_775
	ds_read_b128 v[176:179], v243 offset:16384
	ds_read_b128 v[192:195], v243 offset:17408
	ds_read_b128 v[172:175], v243 offset:18432
	ds_read_b128 v[188:191], v243 offset:19456
	ds_read_b128 v[168:171], v243 offset:20480
	ds_read_b128 v[184:187], v243 offset:21504
	ds_read_b128 v[164:167], v243 offset:22528
	ds_read_b128 v[180:183], v243 offset:23552
.LBB0_775:
	s_add_u32 s38, s28, s34
	s_addc_u32 s39, s29, s35
	s_add_u32 s40, s38, 0x100
	s_addc_u32 s41, s39, 0
	s_add_u32 s88, s72, s34
	s_addc_u32 s89, s73, s35
	s_cmpk_eq_i32 s34, 0xf00
	s_cselect_b64 s[42:43], -1, 0
	s_and_b64 s[38:39], s[42:43], exec
	s_cselect_b32 s39, s17, s89
	s_cselect_b32 s38, s0, s88
	s_mov_b32 m0, s52
	s_cselect_b32 s41, s19, s41
	s_cselect_b32 s40, s21, s40
	v_lshl_add_u64 v[2:3], s[38:39], 0, v[204:205]
	s_add_u32 s88, s38, 0x80000
	global_load_lds_dwordx4 v[2:3], off
	v_lshl_add_u64 v[220:221], s[38:39], 0, v[208:209]
	s_mov_b32 m0, s53
	s_addc_u32 s89, s39, 0
	global_load_lds_dwordx4 v[220:221], off
	v_lshl_add_u64 v[222:223], s[88:89], 0, v[204:205]
	s_mov_b32 m0, s55
	v_lshl_add_u64 v[224:225], s[40:41], 0, v[206:207]
	global_load_lds_dwordx4 v[222:223], off
	v_lshl_add_u64 v[222:223], s[88:89], 0, v[208:209]
	s_mov_b32 m0, s56
	s_and_b64 vcc, exec, s[6:7]
	global_load_lds_dwordx4 v[222:223], off
	v_lshl_add_u64 v[222:223], s[40:41], 0, v[202:203]
	s_mov_b32 m0, s57
	s_nop 0
	global_load_lds_dwordx4 v[222:223], off
	s_mov_b32 m0, s58
	s_nop 0
	global_load_lds_dwordx4 v[224:225], off
	s_waitcnt vmcnt(8)
	s_waitcnt lgkmcnt(0)
	s_barrier
	s_cbranch_vccnz .LBB0_777
	s_waitcnt lgkmcnt(0)
	v_mfma_f32_16x16x32_bf16 v[64:67], v[148:151], v[176:179], v[64:67]
	v_mfma_f32_16x16x32_bf16 v[60:63], v[156:159], v[176:179], v[60:63]
	v_mfma_f32_16x16x32_bf16 v[48:51], v[148:151], v[172:175], v[48:51]
	v_mfma_f32_16x16x32_bf16 v[44:47], v[156:159], v[172:175], v[44:47]
	v_mfma_f32_16x16x32_bf16 v[32:35], v[148:151], v[168:171], v[32:35]
	v_mfma_f32_16x16x32_bf16 v[28:31], v[156:159], v[168:171], v[28:31]
	v_mfma_f32_16x16x32_bf16 v[16:19], v[148:151], v[164:167], v[16:19]
	v_mfma_f32_16x16x32_bf16 v[12:15], v[156:159], v[164:167], v[12:15]
	v_mfma_f32_16x16x32_bf16 v[64:67], v[152:155], v[192:195], v[64:67]
	v_mfma_f32_16x16x32_bf16 v[60:63], v[160:163], v[192:195], v[60:63]
	v_mfma_f32_16x16x32_bf16 v[48:51], v[152:155], v[188:191], v[48:51]
	v_mfma_f32_16x16x32_bf16 v[44:47], v[160:163], v[188:191], v[44:47]
	v_mfma_f32_16x16x32_bf16 v[32:35], v[152:155], v[184:187], v[32:35]
	v_mfma_f32_16x16x32_bf16 v[28:31], v[160:163], v[184:187], v[28:31]
	v_mfma_f32_16x16x32_bf16 v[16:19], v[152:155], v[180:183], v[16:19]
	v_mfma_f32_16x16x32_bf16 v[12:15], v[160:163], v[180:183], v[12:15]
	v_mfma_f32_16x16x32_bf16 v[56:59], v[132:135], v[176:179], v[56:59]
	v_mfma_f32_16x16x32_bf16 v[52:55], v[140:143], v[176:179], v[52:55]
	v_mfma_f32_16x16x32_bf16 v[40:43], v[132:135], v[172:175], v[40:43]
	v_mfma_f32_16x16x32_bf16 v[36:39], v[140:143], v[172:175], v[36:39]
	v_mfma_f32_16x16x32_bf16 v[24:27], v[132:135], v[168:171], v[24:27]
	v_mfma_f32_16x16x32_bf16 v[20:23], v[140:143], v[168:171], v[20:23]
	v_mfma_f32_16x16x32_bf16 v[8:11], v[132:135], v[164:167], v[8:11]
	v_mfma_f32_16x16x32_bf16 v[4:7], v[140:143], v[164:167], v[4:7]
	v_mfma_f32_16x16x32_bf16 v[56:59], v[136:139], v[192:195], v[56:59]
	v_mfma_f32_16x16x32_bf16 v[52:55], v[144:147], v[192:195], v[52:55]
	v_mfma_f32_16x16x32_bf16 v[40:43], v[136:139], v[188:191], v[40:43]
	v_mfma_f32_16x16x32_bf16 v[36:39], v[144:147], v[188:191], v[36:39]
	v_mfma_f32_16x16x32_bf16 v[24:27], v[136:139], v[184:187], v[24:27]
	v_mfma_f32_16x16x32_bf16 v[20:23], v[144:147], v[184:187], v[20:23]
	v_mfma_f32_16x16x32_bf16 v[8:11], v[136:139], v[180:183], v[8:11]
	v_mfma_f32_16x16x32_bf16 v[4:7], v[144:147], v[180:183], v[4:7]
.LBB0_777:
	s_barrier
	v_add_u32_e32 v0, s61, v241
	ds_read_b128 v[148:151], v0
	ds_read_b128 v[152:155], v0 offset:1024
	ds_read_b128 v[156:159], v0 offset:2048
	ds_read_b128 v[160:163], v0 offset:3072
	v_add_u32_e32 v0, s76, v241
	ds_read_b128 v[132:135], v0
	ds_read_b128 v[136:139], v0 offset:1024
	ds_read_b128 v[140:143], v0 offset:2048
	ds_read_b128 v[144:147], v0 offset:3072
	s_and_b64 s[42:43], s[22:23], s[42:43]
	s_and_b64 s[42:43], s[42:43], exec
	s_cselect_b32 s43, s74, s30
	s_cselect_b32 s42, 0, s31
	s_add_u32 s40, s40, s43
	s_addc_u32 s41, s41, s42
	s_mov_b32 m0, s59
	v_lshl_add_u64 v[244:245], s[40:41], 0, v[202:203]
	s_waitcnt lgkmcnt(0)
	ds_read_b128 v[176:179], v243 offset:32768
	ds_read_b128 v[192:195], v243 offset:33792
	ds_read_b128 v[172:175], v243 offset:34816
	ds_read_b128 v[188:191], v243 offset:35840
	ds_read_b128 v[168:171], v243 offset:36864
	ds_read_b128 v[184:187], v243 offset:37888
	ds_read_b128 v[164:167], v243 offset:38912
	ds_read_b128 v[180:183], v243 offset:39936
	global_load_lds_dwordx4 v[244:245], off
	v_lshl_add_u64 v[244:245], s[40:41], 0, v[206:207]
	s_mov_b32 m0, s60
	s_nop 0
	global_load_lds_dwordx4 v[244:245], off
	s_waitcnt vmcnt(8)
	s_waitcnt lgkmcnt(0)
	s_barrier
	s_waitcnt lgkmcnt(0)
	v_mfma_f32_16x16x32_bf16 v[128:131], v[148:151], v[176:179], v[128:131]
	v_mfma_f32_16x16x32_bf16 v[124:127], v[156:159], v[176:179], v[124:127]
	v_mfma_f32_16x16x32_bf16 v[120:123], v[148:151], v[172:175], v[120:123]
	v_mfma_f32_16x16x32_bf16 v[112:115], v[156:159], v[172:175], v[112:115]
	v_mfma_f32_16x16x32_bf16 v[104:107], v[148:151], v[168:171], v[104:107]
	v_mfma_f32_16x16x32_bf16 v[96:99], v[156:159], v[168:171], v[96:99]
	v_mfma_f32_16x16x32_bf16 v[88:91], v[148:151], v[164:167], v[88:91]
	v_mfma_f32_16x16x32_bf16 v[80:83], v[156:159], v[164:167], v[80:83]
	v_mfma_f32_16x16x32_bf16 v[128:131], v[152:155], v[192:195], v[128:131]
	v_mfma_f32_16x16x32_bf16 v[124:127], v[160:163], v[192:195], v[124:127]
	v_mfma_f32_16x16x32_bf16 v[120:123], v[152:155], v[188:191], v[120:123]
	v_mfma_f32_16x16x32_bf16 v[112:115], v[160:163], v[188:191], v[112:115]
	v_mfma_f32_16x16x32_bf16 v[104:107], v[152:155], v[184:187], v[104:107]
	v_mfma_f32_16x16x32_bf16 v[96:99], v[160:163], v[184:187], v[96:99]
	v_mfma_f32_16x16x32_bf16 v[88:91], v[152:155], v[180:183], v[88:91]
	v_mfma_f32_16x16x32_bf16 v[80:83], v[160:163], v[180:183], v[80:83]
	v_mfma_f32_16x16x32_bf16 v[116:119], v[132:135], v[176:179], v[116:119]
	v_mfma_f32_16x16x32_bf16 v[108:111], v[140:143], v[176:179], v[108:111]
	v_mfma_f32_16x16x32_bf16 v[100:103], v[132:135], v[172:175], v[100:103]
	v_mfma_f32_16x16x32_bf16 v[92:95], v[140:143], v[172:175], v[92:95]
	v_mfma_f32_16x16x32_bf16 v[84:87], v[132:135], v[168:171], v[84:87]
	v_mfma_f32_16x16x32_bf16 v[76:79], v[140:143], v[168:171], v[76:79]
	v_mfma_f32_16x16x32_bf16 v[72:75], v[132:135], v[164:167], v[72:75]
	v_mfma_f32_16x16x32_bf16 v[68:71], v[140:143], v[164:167], v[68:71]
	v_mfma_f32_16x16x32_bf16 v[116:119], v[136:139], v[192:195], v[116:119]
	v_mfma_f32_16x16x32_bf16 v[108:111], v[144:147], v[192:195], v[108:111]
	v_mfma_f32_16x16x32_bf16 v[100:103], v[136:139], v[188:191], v[100:103]
	v_mfma_f32_16x16x32_bf16 v[92:95], v[144:147], v[188:191], v[92:95]
	v_mfma_f32_16x16x32_bf16 v[84:87], v[136:139], v[184:187], v[84:87]
	v_mfma_f32_16x16x32_bf16 v[76:79], v[144:147], v[184:187], v[76:79]
	v_mfma_f32_16x16x32_bf16 v[72:75], v[136:139], v[180:183], v[72:75]
	v_mfma_f32_16x16x32_bf16 v[68:71], v[144:147], v[180:183], v[68:71]
	s_barrier
	s_and_b64 vcc, exec, s[6:7]
	s_mov_b64 s[88:89], s[86:87]
	s_cbranch_vccnz .LBB0_779
	ds_read_b128 v[176:179], v243 offset:49152
	ds_read_b128 v[192:195], v243 offset:50176
	ds_read_b128 v[172:175], v243 offset:51200
	ds_read_b128 v[188:191], v243 offset:52224
	ds_read_b128 v[168:171], v243 offset:53248
	ds_read_b128 v[184:187], v243 offset:54272
	ds_read_b128 v[164:167], v243 offset:55296
	ds_read_b128 v[180:183], v243 offset:56320
.LBB0_779:
	s_mov_b32 m0, s66
	v_lshl_add_u64 v[2:3], v[2:3], 0, s[44:45]
	s_add_u32 s38, s38, 0x80080
	global_load_lds_dwordx4 v[2:3], off
	v_lshl_add_u64 v[2:3], v[220:221], 0, s[44:45]
	s_mov_b32 m0, s67
	s_addc_u32 s39, s39, 0
	global_load_lds_dwordx4 v[2:3], off
	v_lshl_add_u64 v[2:3], s[38:39], 0, v[204:205]
	s_mov_b32 m0, s77
	s_and_b64 vcc, exec, s[6:7]
	global_load_lds_dwordx4 v[2:3], off
	v_lshl_add_u64 v[2:3], s[38:39], 0, v[208:209]
	s_mov_b32 m0, s80
	s_nop 0
	global_load_lds_dwordx4 v[2:3], off
	v_lshl_add_u64 v[2:3], v[222:223], 0, s[44:45]
	s_mov_b32 m0, s70
	s_nop 0
	global_load_lds_dwordx4 v[2:3], off
	v_lshl_add_u64 v[2:3], v[224:225], 0, s[44:45]
	s_mov_b32 m0, s71
	s_nop 0
	global_load_lds_dwordx4 v[2:3], off
	s_waitcnt vmcnt(8)
	s_waitcnt lgkmcnt(0)
	s_barrier
	s_cbranch_vccnz .LBB0_772
	s_waitcnt lgkmcnt(0)
	v_mfma_f32_16x16x32_bf16 v[64:67], v[148:151], v[176:179], v[64:67]
	v_mfma_f32_16x16x32_bf16 v[60:63], v[156:159], v[176:179], v[60:63]
	v_mfma_f32_16x16x32_bf16 v[48:51], v[148:151], v[172:175], v[48:51]
	v_mfma_f32_16x16x32_bf16 v[44:47], v[156:159], v[172:175], v[44:47]
	v_mfma_f32_16x16x32_bf16 v[32:35], v[148:151], v[168:171], v[32:35]
	v_mfma_f32_16x16x32_bf16 v[28:31], v[156:159], v[168:171], v[28:31]
	v_mfma_f32_16x16x32_bf16 v[16:19], v[148:151], v[164:167], v[16:19]
	v_mfma_f32_16x16x32_bf16 v[12:15], v[156:159], v[164:167], v[12:15]
	v_mfma_f32_16x16x32_bf16 v[64:67], v[152:155], v[192:195], v[64:67]
	v_mfma_f32_16x16x32_bf16 v[60:63], v[160:163], v[192:195], v[60:63]
	v_mfma_f32_16x16x32_bf16 v[48:51], v[152:155], v[188:191], v[48:51]
	v_mfma_f32_16x16x32_bf16 v[44:47], v[160:163], v[188:191], v[44:47]
	v_mfma_f32_16x16x32_bf16 v[32:35], v[152:155], v[184:187], v[32:35]
	v_mfma_f32_16x16x32_bf16 v[28:31], v[160:163], v[184:187], v[28:31]
	v_mfma_f32_16x16x32_bf16 v[16:19], v[152:155], v[180:183], v[16:19]
	v_mfma_f32_16x16x32_bf16 v[12:15], v[160:163], v[180:183], v[12:15]
	v_mfma_f32_16x16x32_bf16 v[56:59], v[132:135], v[176:179], v[56:59]
	v_mfma_f32_16x16x32_bf16 v[52:55], v[140:143], v[176:179], v[52:55]
	v_mfma_f32_16x16x32_bf16 v[40:43], v[132:135], v[172:175], v[40:43]
	v_mfma_f32_16x16x32_bf16 v[36:39], v[140:143], v[172:175], v[36:39]
	v_mfma_f32_16x16x32_bf16 v[24:27], v[132:135], v[168:171], v[24:27]
	v_mfma_f32_16x16x32_bf16 v[20:23], v[140:143], v[168:171], v[20:23]
	v_mfma_f32_16x16x32_bf16 v[8:11], v[132:135], v[164:167], v[8:11]
	v_mfma_f32_16x16x32_bf16 v[2:5], v[140:143], v[164:167], v[4:7]
	v_mfma_f32_16x16x32_bf16 v[56:59], v[136:139], v[192:195], v[56:59]
	v_mfma_f32_16x16x32_bf16 v[52:55], v[144:147], v[192:195], v[52:55]
	v_mfma_f32_16x16x32_bf16 v[40:43], v[136:139], v[188:191], v[40:43]
	v_mfma_f32_16x16x32_bf16 v[36:39], v[144:147], v[188:191], v[36:39]
	v_mfma_f32_16x16x32_bf16 v[24:27], v[136:139], v[184:187], v[24:27]
	v_mfma_f32_16x16x32_bf16 v[20:23], v[144:147], v[184:187], v[20:23]
	v_mfma_f32_16x16x32_bf16 v[8:11], v[136:139], v[180:183], v[8:11]
	v_mfma_f32_16x16x32_bf16 v[4:7], v[144:147], v[180:183], v[2:5]
	s_branch .LBB0_772

.LBB0_1468:
	v_add_u32_e32 v110, s27, v159
	v_add_u32_e32 v126, s30, v159
	ds_read_b128 v[98:101], v110
	ds_read_b128 v[102:105], v110 offset:1024
	ds_read_b128 v[106:109], v110 offset:2048
	ds_read_b128 v[110:113], v110 offset:3072
	ds_read_b128 v[114:117], v126
	ds_read_b128 v[118:121], v126 offset:1024
	ds_read_b128 v[122:125], v126 offset:2048
	ds_read_b128 v[126:129], v126 offset:3072
	s_add_u32 s8, s10, 0x100
	s_addc_u32 s9, s11, 0
	s_cmp_eq_u32 s67, 28
	s_cselect_b32 s71, s19, s9
	s_cselect_b32 s70, s18, s8
	s_cselect_b32 s23, s0, s66
	s_cselect_b32 s22, s17, s61
	v_lshl_add_u64 v[172:173], s[10:11], 0, v[148:149]
	s_add_i32 m0, s35, 0xc000
	ds_read_b128 v[130:133], v162
	ds_read_b128 v[134:137], v162 offset:1024
	ds_read_b128 v[138:141], v162 offset:2048
	ds_read_b128 v[142:145], v162 offset:3072
	ds_read_b128 v[150:153], v162 offset:4096
	ds_read_b128 v[154:157], v162 offset:5120
	ds_read_b128 v[164:167], v162 offset:6144
	ds_read_b128 v[168:171], v162 offset:7168
	global_load_lds_dwordx4 v[172:173], off
	s_waitcnt vmcnt(7)
	s_waitcnt lgkmcnt(0)
	s_barrier
	s_waitcnt lgkmcnt(0)
	v_mfma_f32_16x16x32_bf16 v[94:97], v[98:101], v[130:133], v[94:97]
	v_mfma_f32_16x16x32_bf16 v[90:93], v[106:109], v[130:133], v[90:93]
	v_mfma_f32_16x16x32_bf16 v[78:81], v[98:101], v[138:141], v[78:81]
	v_mfma_f32_16x16x32_bf16 v[74:77], v[106:109], v[138:141], v[74:77]
	v_mfma_f32_16x16x32_bf16 v[62:65], v[98:101], v[150:153], v[62:65]
	v_mfma_f32_16x16x32_bf16 v[58:61], v[106:109], v[150:153], v[58:61]
	v_mfma_f32_16x16x32_bf16 v[46:49], v[98:101], v[164:167], v[46:49]
	v_mfma_f32_16x16x32_bf16 v[42:45], v[106:109], v[164:167], v[42:45]
	v_mfma_f32_16x16x32_bf16 v[94:97], v[102:105], v[134:137], v[94:97]
	v_mfma_f32_16x16x32_bf16 v[90:93], v[110:113], v[134:137], v[90:93]
	v_mfma_f32_16x16x32_bf16 v[78:81], v[102:105], v[142:145], v[78:81]
	v_mfma_f32_16x16x32_bf16 v[74:77], v[110:113], v[142:145], v[74:77]
	v_mfma_f32_16x16x32_bf16 v[62:65], v[102:105], v[154:157], v[62:65]
	v_mfma_f32_16x16x32_bf16 v[58:61], v[110:113], v[154:157], v[58:61]
	v_mfma_f32_16x16x32_bf16 v[46:49], v[102:105], v[168:171], v[46:49]
	v_mfma_f32_16x16x32_bf16 v[42:45], v[110:113], v[168:171], v[42:45]
	v_mfma_f32_16x16x32_bf16 v[86:89], v[114:117], v[130:133], v[86:89]
	v_mfma_f32_16x16x32_bf16 v[82:85], v[122:125], v[130:133], v[82:85]
	v_mfma_f32_16x16x32_bf16 v[70:73], v[114:117], v[138:141], v[70:73]
	v_mfma_f32_16x16x32_bf16 v[66:69], v[122:125], v[138:141], v[66:69]
	v_mfma_f32_16x16x32_bf16 v[54:57], v[114:117], v[150:153], v[54:57]
	v_mfma_f32_16x16x32_bf16 v[50:53], v[122:125], v[150:153], v[50:53]
	v_mfma_f32_16x16x32_bf16 v[38:41], v[114:117], v[164:167], v[38:41]
	v_mfma_f32_16x16x32_bf16 v[34:37], v[122:125], v[164:167], v[34:37]
	v_mfma_f32_16x16x32_bf16 v[86:89], v[118:121], v[134:137], v[86:89]
	v_mfma_f32_16x16x32_bf16 v[82:85], v[126:129], v[134:137], v[82:85]
	v_mfma_f32_16x16x32_bf16 v[70:73], v[118:121], v[142:145], v[70:73]
	v_mfma_f32_16x16x32_bf16 v[66:69], v[126:129], v[142:145], v[66:69]
	v_mfma_f32_16x16x32_bf16 v[54:57], v[118:121], v[154:157], v[54:57]
	v_mfma_f32_16x16x32_bf16 v[50:53], v[126:129], v[154:157], v[50:53]
	v_mfma_f32_16x16x32_bf16 v[38:41], v[118:121], v[168:171], v[38:41]
	v_mfma_f32_16x16x32_bf16 v[34:37], v[126:129], v[168:171], v[34:37]
	s_barrier
	s_mov_b32 m0, s28
	v_lshl_add_u64 v[172:173], s[22:23], 0, v[0:1]
	s_add_u32 s10, s22, 0x80000
	ds_read_b128 v[130:133], v163 offset:16384
	ds_read_b128 v[134:137], v163 offset:17408
	ds_read_b128 v[138:141], v163 offset:18432
	ds_read_b128 v[142:145], v163 offset:19456
	global_load_lds_dwordx4 v[172:173], off
	v_lshl_add_u64 v[174:175], s[22:23], 0, v[146:147]
	s_mov_b32 m0, s29
	s_addc_u32 s11, s23, 0
	global_load_lds_dwordx4 v[174:175], off
	v_lshl_add_u64 v[150:151], s[10:11], 0, v[0:1]
	s_mov_b32 m0, s31
	v_lshl_add_u64 v[176:177], s[70:71], 0, v[0:1]
	global_load_lds_dwordx4 v[150:151], off
	v_lshl_add_u64 v[150:151], s[10:11], 0, v[146:147]
	s_mov_b32 m0, s34
	v_lshl_add_u64 v[178:179], s[70:71], 0, v[146:147]
	global_load_lds_dwordx4 v[150:151], off
	s_mov_b32 m0, s35
	s_nop 0
	global_load_lds_dwordx4 v[176:177], off
	s_mov_b32 m0, s36
	s_nop 0
	global_load_lds_dwordx4 v[178:179], off
	s_waitcnt vmcnt(7)
	s_waitcnt lgkmcnt(0)
	s_barrier
	s_waitcnt lgkmcnt(0)
	v_mfma_f32_16x16x32_bf16 v[30:33], v[98:101], v[130:133], v[30:33]
	v_mfma_f32_16x16x32_bf16 v[26:29], v[106:109], v[130:133], v[26:29]
	v_mfma_f32_16x16x32_bf16 v[14:17], v[98:101], v[138:141], v[14:17]
	v_mfma_f32_16x16x32_bf16 v[10:13], v[106:109], v[138:141], v[10:13]
	v_mfma_f32_16x16x32_bf16 v[30:33], v[102:105], v[134:137], v[30:33]
	v_mfma_f32_16x16x32_bf16 v[26:29], v[110:113], v[134:137], v[26:29]
	v_mfma_f32_16x16x32_bf16 v[14:17], v[102:105], v[142:145], v[14:17]
	v_mfma_f32_16x16x32_bf16 v[10:13], v[110:113], v[142:145], v[10:13]
	v_mfma_f32_16x16x32_bf16 v[22:25], v[114:117], v[130:133], v[22:25]
	v_mfma_f32_16x16x32_bf16 v[18:21], v[122:125], v[130:133], v[18:21]
	v_mfma_f32_16x16x32_bf16 v[6:9], v[114:117], v[138:141], v[6:9]
	v_mfma_f32_16x16x32_bf16 v[2:5], v[122:125], v[138:141], v[2:5]
	v_mfma_f32_16x16x32_bf16 v[22:25], v[118:121], v[134:137], v[22:25]
	v_mfma_f32_16x16x32_bf16 v[18:21], v[126:129], v[134:137], v[18:21]
	v_mfma_f32_16x16x32_bf16 v[6:9], v[118:121], v[142:145], v[6:9]
	v_mfma_f32_16x16x32_bf16 v[2:5], v[126:129], v[142:145], v[2:5]
	s_barrier
	v_add_u32_e32 v110, s43, v159
	v_add_u32_e32 v126, s53, v159
	ds_read_b128 v[98:101], v110
	ds_read_b128 v[102:105], v110 offset:1024
	ds_read_b128 v[106:109], v110 offset:2048
	ds_read_b128 v[110:113], v110 offset:3072
	ds_read_b128 v[114:117], v126
	ds_read_b128 v[118:121], v126 offset:1024
	ds_read_b128 v[122:125], v126 offset:2048
	ds_read_b128 v[126:129], v126 offset:3072
	v_lshl_add_u64 v[180:181], v[176:177], 0, s[62:63]
	s_mov_b32 m0, s37
	ds_read_b128 v[130:133], v162 offset:32768
	ds_read_b128 v[134:137], v162 offset:33792
	ds_read_b128 v[138:141], v162 offset:34816
	ds_read_b128 v[142:145], v162 offset:35840
	ds_read_b128 v[150:153], v162 offset:36864
	ds_read_b128 v[154:157], v162 offset:37888
	ds_read_b128 v[164:167], v162 offset:38912
	ds_read_b128 v[168:171], v162 offset:39936
	global_load_lds_dwordx4 v[180:181], off
	s_waitcnt vmcnt(7)
	s_waitcnt lgkmcnt(0)
	s_barrier
	s_waitcnt lgkmcnt(0)
	v_mfma_f32_16x16x32_bf16 v[94:97], v[98:101], v[130:133], v[94:97]
	v_mfma_f32_16x16x32_bf16 v[90:93], v[106:109], v[130:133], v[90:93]
	v_mfma_f32_16x16x32_bf16 v[78:81], v[98:101], v[138:141], v[78:81]
	v_mfma_f32_16x16x32_bf16 v[74:77], v[106:109], v[138:141], v[74:77]
	v_mfma_f32_16x16x32_bf16 v[62:65], v[98:101], v[150:153], v[62:65]
	v_mfma_f32_16x16x32_bf16 v[58:61], v[106:109], v[150:153], v[58:61]
	v_mfma_f32_16x16x32_bf16 v[46:49], v[98:101], v[164:167], v[46:49]
	v_mfma_f32_16x16x32_bf16 v[42:45], v[106:109], v[164:167], v[42:45]
	v_mfma_f32_16x16x32_bf16 v[94:97], v[102:105], v[134:137], v[94:97]
	v_mfma_f32_16x16x32_bf16 v[90:93], v[110:113], v[134:137], v[90:93]
	v_mfma_f32_16x16x32_bf16 v[78:81], v[102:105], v[142:145], v[78:81]
	v_mfma_f32_16x16x32_bf16 v[74:77], v[110:113], v[142:145], v[74:77]
	v_mfma_f32_16x16x32_bf16 v[62:65], v[102:105], v[154:157], v[62:65]
	v_mfma_f32_16x16x32_bf16 v[58:61], v[110:113], v[154:157], v[58:61]
	v_mfma_f32_16x16x32_bf16 v[46:49], v[102:105], v[168:171], v[46:49]
	v_mfma_f32_16x16x32_bf16 v[42:45], v[110:113], v[168:171], v[42:45]
	v_mfma_f32_16x16x32_bf16 v[86:89], v[114:117], v[130:133], v[86:89]
	v_mfma_f32_16x16x32_bf16 v[82:85], v[122:125], v[130:133], v[82:85]
	v_mfma_f32_16x16x32_bf16 v[70:73], v[114:117], v[138:141], v[70:73]
	v_mfma_f32_16x16x32_bf16 v[66:69], v[122:125], v[138:141], v[66:69]
	v_mfma_f32_16x16x32_bf16 v[54:57], v[114:117], v[150:153], v[54:57]
	v_mfma_f32_16x16x32_bf16 v[50:53], v[122:125], v[150:153], v[50:53]
	v_mfma_f32_16x16x32_bf16 v[38:41], v[114:117], v[164:167], v[38:41]
	v_mfma_f32_16x16x32_bf16 v[34:37], v[122:125], v[164:167], v[34:37]
	v_mfma_f32_16x16x32_bf16 v[86:89], v[118:121], v[134:137], v[86:89]
	v_mfma_f32_16x16x32_bf16 v[82:85], v[126:129], v[134:137], v[82:85]
	v_mfma_f32_16x16x32_bf16 v[70:73], v[118:121], v[142:145], v[70:73]
	v_mfma_f32_16x16x32_bf16 v[66:69], v[126:129], v[142:145], v[66:69]
	v_mfma_f32_16x16x32_bf16 v[54:57], v[118:121], v[154:157], v[54:57]
	v_mfma_f32_16x16x32_bf16 v[50:53], v[126:129], v[154:157], v[50:53]
	v_mfma_f32_16x16x32_bf16 v[38:41], v[118:121], v[168:171], v[38:41]
	v_mfma_f32_16x16x32_bf16 v[34:37], v[126:129], v[168:171], v[34:37]
	s_barrier
	s_mov_b32 m0, s49
	v_lshl_add_u64 v[150:151], v[172:173], 0, s[44:45]
	s_add_u32 s10, s22, 0x80080
	ds_read_b128 v[130:133], v163 offset:49152
	ds_read_b128 v[134:137], v163 offset:50176
	ds_read_b128 v[138:141], v163 offset:51200
	ds_read_b128 v[142:145], v163 offset:52224
	global_load_lds_dwordx4 v[150:151], off
	v_lshl_add_u64 v[150:151], v[174:175], 0, s[44:45]
	s_mov_b32 m0, s50
	s_addc_u32 s11, s23, 0
	global_load_lds_dwordx4 v[150:151], off
	v_lshl_add_u64 v[150:151], s[10:11], 0, v[0:1]
	s_mov_b32 m0, s54
	s_nop 0
	global_load_lds_dwordx4 v[150:151], off
	v_lshl_add_u64 v[150:151], s[10:11], 0, v[146:147]
	s_mov_b32 m0, s55
	s_nop 0
	global_load_lds_dwordx4 v[150:151], off
	v_lshl_add_u64 v[150:151], v[176:177], 0, s[44:45]
	s_mov_b32 m0, s51
	s_nop 0
	global_load_lds_dwordx4 v[150:151], off
	v_lshl_add_u64 v[150:151], v[178:179], 0, s[44:45]
	s_mov_b32 m0, s52
	s_nop 0
	global_load_lds_dwordx4 v[150:151], off
	s_waitcnt vmcnt(7)
	s_waitcnt lgkmcnt(0)
	s_barrier
	s_waitcnt lgkmcnt(0)
	v_mfma_f32_16x16x32_bf16 v[30:33], v[98:101], v[130:133], v[30:33]
	v_mfma_f32_16x16x32_bf16 v[26:29], v[106:109], v[130:133], v[26:29]
	v_mfma_f32_16x16x32_bf16 v[14:17], v[98:101], v[138:141], v[14:17]
	v_mfma_f32_16x16x32_bf16 v[10:13], v[106:109], v[138:141], v[10:13]
	v_mfma_f32_16x16x32_bf16 v[30:33], v[102:105], v[134:137], v[30:33]
	v_mfma_f32_16x16x32_bf16 v[26:29], v[110:113], v[134:137], v[26:29]
	v_mfma_f32_16x16x32_bf16 v[14:17], v[102:105], v[142:145], v[14:17]
	v_mfma_f32_16x16x32_bf16 v[10:13], v[110:113], v[142:145], v[10:13]
	v_mfma_f32_16x16x32_bf16 v[22:25], v[114:117], v[130:133], v[22:25]
	v_mfma_f32_16x16x32_bf16 v[18:21], v[122:125], v[130:133], v[18:21]
	v_mfma_f32_16x16x32_bf16 v[6:9], v[114:117], v[138:141], v[6:9]
	v_mfma_f32_16x16x32_bf16 v[2:5], v[122:125], v[138:141], v[2:5]
	v_mfma_f32_16x16x32_bf16 v[22:25], v[118:121], v[134:137], v[22:25]
	v_mfma_f32_16x16x32_bf16 v[18:21], v[126:129], v[134:137], v[18:21]
	v_mfma_f32_16x16x32_bf16 v[6:9], v[118:121], v[142:145], v[6:9]
	v_mfma_f32_16x16x32_bf16 v[2:5], v[126:129], v[142:145], v[2:5]
	s_barrier
	s_add_i32 s67, s67, 2
	s_add_u32 s61, s61, 0x100
	s_addc_u32 s66, s66, 0
	s_cmp_gt_u32 s67, 29
	s_mov_b64 s[10:11], s[8:9]
	s_cbranch_scc0 .LBB0_1468
	s_and_b64 vcc, exec, s[14:15]
	s_cbranch_vccz .LBB0_1471
	s_barrier

.LBB0_1609:
	v_add_u32_e32 v0, s23, v225
	ds_read_b128 v[148:151], v0
	ds_read_b128 v[152:155], v0 offset:1024
	ds_read_b128 v[156:159], v0 offset:2048
	ds_read_b128 v[160:163], v0 offset:3072
	v_add_u32_e32 v0, s50, v225
	ds_read_b128 v[132:135], v0
	ds_read_b128 v[136:139], v0 offset:1024
	ds_read_b128 v[140:143], v0 offset:2048
	ds_read_b128 v[144:147], v0 offset:3072
	v_lshl_add_u64 v[2:3], v[216:217], 0, s[28:29]
	s_add_i32 m0, s53, 0xc000
	s_waitcnt lgkmcnt(0)
	ds_read_b128 v[176:179], v241
	ds_read_b128 v[192:195], v241 offset:1024
	ds_read_b128 v[172:175], v241 offset:2048
	ds_read_b128 v[188:191], v241 offset:3072
	ds_read_b128 v[168:171], v241 offset:4096
	ds_read_b128 v[184:187], v241 offset:5120
	ds_read_b128 v[164:167], v241 offset:6144
	ds_read_b128 v[180:183], v241 offset:7168
	global_load_lds_dwordx4 v[2:3], off
	v_lshl_add_u64 v[2:3], v[214:215], 0, s[28:29]
	s_add_i32 m0, s53, 0xe000
	s_nop 0
	global_load_lds_dwordx4 v[2:3], off
	s_waitcnt vmcnt(8)
	s_waitcnt lgkmcnt(0)
	s_barrier
	s_waitcnt lgkmcnt(0)
	v_mfma_f32_16x16x32_bf16 v[128:131], v[148:151], v[176:179], v[128:131]
	v_mfma_f32_16x16x32_bf16 v[120:123], v[156:159], v[176:179], v[120:123]
	v_mfma_f32_16x16x32_bf16 v[112:115], v[148:151], v[172:175], v[112:115]
	v_mfma_f32_16x16x32_bf16 v[104:107], v[156:159], v[172:175], v[104:107]
	v_mfma_f32_16x16x32_bf16 v[96:99], v[148:151], v[168:171], v[96:99]
	v_mfma_f32_16x16x32_bf16 v[88:91], v[156:159], v[168:171], v[88:91]
	v_mfma_f32_16x16x32_bf16 v[80:83], v[148:151], v[164:167], v[80:83]
	v_mfma_f32_16x16x32_bf16 v[72:75], v[156:159], v[164:167], v[72:75]
	v_mfma_f32_16x16x32_bf16 v[128:131], v[152:155], v[192:195], v[128:131]
	v_mfma_f32_16x16x32_bf16 v[120:123], v[160:163], v[192:195], v[120:123]
	v_mfma_f32_16x16x32_bf16 v[112:115], v[152:155], v[188:191], v[112:115]
	v_mfma_f32_16x16x32_bf16 v[104:107], v[160:163], v[188:191], v[104:107]
	v_mfma_f32_16x16x32_bf16 v[96:99], v[152:155], v[184:187], v[96:99]
	v_mfma_f32_16x16x32_bf16 v[88:91], v[160:163], v[184:187], v[88:91]
	v_mfma_f32_16x16x32_bf16 v[80:83], v[152:155], v[180:183], v[80:83]
	v_mfma_f32_16x16x32_bf16 v[72:75], v[160:163], v[180:183], v[72:75]
	v_mfma_f32_16x16x32_bf16 v[124:127], v[132:135], v[176:179], v[124:127]
	v_mfma_f32_16x16x32_bf16 v[116:119], v[140:143], v[176:179], v[116:119]
	v_mfma_f32_16x16x32_bf16 v[108:111], v[132:135], v[172:175], v[108:111]
	v_mfma_f32_16x16x32_bf16 v[100:103], v[140:143], v[172:175], v[100:103]
	v_mfma_f32_16x16x32_bf16 v[92:95], v[132:135], v[168:171], v[92:95]
	v_mfma_f32_16x16x32_bf16 v[84:87], v[140:143], v[168:171], v[84:87]
	v_mfma_f32_16x16x32_bf16 v[76:79], v[132:135], v[164:167], v[76:79]
	v_mfma_f32_16x16x32_bf16 v[68:71], v[140:143], v[164:167], v[68:71]
	v_mfma_f32_16x16x32_bf16 v[124:127], v[136:139], v[192:195], v[124:127]
	v_mfma_f32_16x16x32_bf16 v[116:119], v[144:147], v[192:195], v[116:119]
	v_mfma_f32_16x16x32_bf16 v[108:111], v[136:139], v[188:191], v[108:111]
	v_mfma_f32_16x16x32_bf16 v[100:103], v[144:147], v[188:191], v[100:103]
	v_mfma_f32_16x16x32_bf16 v[92:95], v[136:139], v[184:187], v[92:95]
	v_mfma_f32_16x16x32_bf16 v[84:87], v[144:147], v[184:187], v[84:87]
	v_mfma_f32_16x16x32_bf16 v[76:79], v[136:139], v[180:183], v[76:79]
	v_mfma_f32_16x16x32_bf16 v[68:71], v[144:147], v[180:183], v[68:71]
	s_barrier
	v_cndmask_b32_e64 v0, 0, 1, s[30:31]
	v_cmp_ne_u32_e64 s[4:5], 1, v0
	s_andn2_b64 vcc, exec, s[30:31]
	s_cbranch_vccnz .LBB0_1611
	ds_read_b128 v[176:179], v241 offset:16384
	ds_read_b128 v[192:195], v241 offset:17408
	ds_read_b128 v[172:175], v241 offset:18432
	ds_read_b128 v[188:191], v241 offset:19456
	ds_read_b128 v[168:171], v241 offset:20480
	ds_read_b128 v[184:187], v241 offset:21504
	ds_read_b128 v[164:167], v241 offset:22528
	ds_read_b128 v[180:183], v241 offset:23552
.LBB0_1611:
	s_add_u32 s34, s24, s28
	s_addc_u32 s35, s25, s29
	s_add_u32 s36, s34, 0x100
	s_addc_u32 s37, s35, 0
	s_add_u32 s88, s72, s28
	s_addc_u32 s89, s73, s29
	s_cmpk_eq_i32 s28, 0xf00
	s_cselect_b64 s[38:39], -1, 0
	s_and_b64 s[34:35], s[38:39], exec
	s_cselect_b32 s35, s13, s89
	s_cselect_b32 s34, s0, s88
	s_mov_b32 m0, s43
	s_cselect_b32 s37, s15, s37
	s_cselect_b32 s36, s81, s36
	v_lshl_add_u64 v[2:3], s[34:35], 0, v[204:205]
	s_add_u32 s88, s34, 0x80000
	global_load_lds_dwordx4 v[2:3], off
	v_lshl_add_u64 v[218:219], s[34:35], 0, v[208:209]
	s_mov_b32 m0, s49
	s_addc_u32 s89, s35, 0
	global_load_lds_dwordx4 v[218:219], off
	v_lshl_add_u64 v[220:221], s[88:89], 0, v[204:205]
	s_mov_b32 m0, s51
	v_lshl_add_u64 v[222:223], s[36:37], 0, v[206:207]
	global_load_lds_dwordx4 v[220:221], off
	v_lshl_add_u64 v[220:221], s[88:89], 0, v[208:209]
	s_mov_b32 m0, s52
	s_and_b64 vcc, exec, s[4:5]
	global_load_lds_dwordx4 v[220:221], off
	v_lshl_add_u64 v[220:221], s[36:37], 0, v[202:203]
	s_mov_b32 m0, s53
	s_nop 0
	global_load_lds_dwordx4 v[220:221], off
	s_mov_b32 m0, s54
	s_nop 0
	global_load_lds_dwordx4 v[222:223], off
	s_waitcnt vmcnt(8)
	s_waitcnt lgkmcnt(0)
	s_barrier
	s_cbranch_vccnz .LBB0_1613
	s_waitcnt lgkmcnt(0)
	v_mfma_f32_16x16x32_bf16 v[64:67], v[148:151], v[176:179], v[64:67]
	v_mfma_f32_16x16x32_bf16 v[56:59], v[156:159], v[176:179], v[56:59]
	v_mfma_f32_16x16x32_bf16 v[48:51], v[148:151], v[172:175], v[48:51]
	v_mfma_f32_16x16x32_bf16 v[40:43], v[156:159], v[172:175], v[40:43]
	v_mfma_f32_16x16x32_bf16 v[32:35], v[148:151], v[168:171], v[32:35]
	v_mfma_f32_16x16x32_bf16 v[24:27], v[156:159], v[168:171], v[24:27]
	v_mfma_f32_16x16x32_bf16 v[16:19], v[148:151], v[164:167], v[16:19]
	v_mfma_f32_16x16x32_bf16 v[8:11], v[156:159], v[164:167], v[8:11]
	v_mfma_f32_16x16x32_bf16 v[64:67], v[152:155], v[192:195], v[64:67]
	v_mfma_f32_16x16x32_bf16 v[56:59], v[160:163], v[192:195], v[56:59]
	v_mfma_f32_16x16x32_bf16 v[48:51], v[152:155], v[188:191], v[48:51]
	v_mfma_f32_16x16x32_bf16 v[40:43], v[160:163], v[188:191], v[40:43]
	v_mfma_f32_16x16x32_bf16 v[32:35], v[152:155], v[184:187], v[32:35]
	v_mfma_f32_16x16x32_bf16 v[24:27], v[160:163], v[184:187], v[24:27]
	v_mfma_f32_16x16x32_bf16 v[16:19], v[152:155], v[180:183], v[16:19]
	v_mfma_f32_16x16x32_bf16 v[8:11], v[160:163], v[180:183], v[8:11]
	v_mfma_f32_16x16x32_bf16 v[60:63], v[132:135], v[176:179], v[60:63]
	v_mfma_f32_16x16x32_bf16 v[52:55], v[140:143], v[176:179], v[52:55]
	v_mfma_f32_16x16x32_bf16 v[44:47], v[132:135], v[172:175], v[44:47]
	v_mfma_f32_16x16x32_bf16 v[36:39], v[140:143], v[172:175], v[36:39]
	v_mfma_f32_16x16x32_bf16 v[28:31], v[132:135], v[168:171], v[28:31]
	v_mfma_f32_16x16x32_bf16 v[20:23], v[140:143], v[168:171], v[20:23]
	v_mfma_f32_16x16x32_bf16 v[12:15], v[132:135], v[164:167], v[12:15]
	v_mfma_f32_16x16x32_bf16 v[4:7], v[140:143], v[164:167], v[4:7]
	v_mfma_f32_16x16x32_bf16 v[60:63], v[136:139], v[192:195], v[60:63]
	v_mfma_f32_16x16x32_bf16 v[52:55], v[144:147], v[192:195], v[52:55]
	v_mfma_f32_16x16x32_bf16 v[44:47], v[136:139], v[188:191], v[44:47]
	v_mfma_f32_16x16x32_bf16 v[36:39], v[144:147], v[188:191], v[36:39]
	v_mfma_f32_16x16x32_bf16 v[28:31], v[136:139], v[184:187], v[28:31]
	v_mfma_f32_16x16x32_bf16 v[20:23], v[144:147], v[184:187], v[20:23]
	v_mfma_f32_16x16x32_bf16 v[12:15], v[136:139], v[180:183], v[12:15]
	v_mfma_f32_16x16x32_bf16 v[4:7], v[144:147], v[180:183], v[4:7]
.LBB0_1613:
	s_barrier
	v_add_u32_e32 v0, s57, v225
	ds_read_b128 v[148:151], v0
	ds_read_b128 v[152:155], v0 offset:1024
	ds_read_b128 v[156:159], v0 offset:2048
	ds_read_b128 v[160:163], v0 offset:3072
	v_add_u32_e32 v0, s66, v225
	ds_read_b128 v[132:135], v0
	ds_read_b128 v[136:139], v0 offset:1024
	ds_read_b128 v[140:143], v0 offset:2048
	ds_read_b128 v[144:147], v0 offset:3072
	s_and_b64 s[38:39], s[16:17], s[38:39]
	s_and_b64 s[38:39], s[38:39], exec
	s_cselect_b32 s39, s74, s26
	s_cselect_b32 s38, 0, s27
	s_add_u32 s36, s36, s39
	s_addc_u32 s37, s37, s38
	s_mov_b32 m0, s55
	v_lshl_add_u64 v[242:243], s[36:37], 0, v[202:203]
	s_waitcnt lgkmcnt(0)
	ds_read_b128 v[176:179], v241 offset:32768
	ds_read_b128 v[192:195], v241 offset:33792
	ds_read_b128 v[172:175], v241 offset:34816
	ds_read_b128 v[188:191], v241 offset:35840
	ds_read_b128 v[168:171], v241 offset:36864
	ds_read_b128 v[184:187], v241 offset:37888
	ds_read_b128 v[164:167], v241 offset:38912
	ds_read_b128 v[180:183], v241 offset:39936
	global_load_lds_dwordx4 v[242:243], off
	v_lshl_add_u64 v[242:243], s[36:37], 0, v[206:207]
	s_mov_b32 m0, s56
	s_nop 0
	global_load_lds_dwordx4 v[242:243], off
	s_waitcnt vmcnt(8)
	s_waitcnt lgkmcnt(0)
	s_barrier
	s_waitcnt lgkmcnt(0)
	v_mfma_f32_16x16x32_bf16 v[128:131], v[148:151], v[176:179], v[128:131]
	v_mfma_f32_16x16x32_bf16 v[120:123], v[156:159], v[176:179], v[120:123]
	v_mfma_f32_16x16x32_bf16 v[112:115], v[148:151], v[172:175], v[112:115]
	v_mfma_f32_16x16x32_bf16 v[104:107], v[156:159], v[172:175], v[104:107]
	v_mfma_f32_16x16x32_bf16 v[96:99], v[148:151], v[168:171], v[96:99]
	v_mfma_f32_16x16x32_bf16 v[88:91], v[156:159], v[168:171], v[88:91]
	v_mfma_f32_16x16x32_bf16 v[80:83], v[148:151], v[164:167], v[80:83]
	v_mfma_f32_16x16x32_bf16 v[72:75], v[156:159], v[164:167], v[72:75]
	v_mfma_f32_16x16x32_bf16 v[128:131], v[152:155], v[192:195], v[128:131]
	v_mfma_f32_16x16x32_bf16 v[120:123], v[160:163], v[192:195], v[120:123]
	v_mfma_f32_16x16x32_bf16 v[112:115], v[152:155], v[188:191], v[112:115]
	v_mfma_f32_16x16x32_bf16 v[104:107], v[160:163], v[188:191], v[104:107]
	v_mfma_f32_16x16x32_bf16 v[96:99], v[152:155], v[184:187], v[96:99]
	v_mfma_f32_16x16x32_bf16 v[88:91], v[160:163], v[184:187], v[88:91]
	v_mfma_f32_16x16x32_bf16 v[80:83], v[152:155], v[180:183], v[80:83]
	v_mfma_f32_16x16x32_bf16 v[72:75], v[160:163], v[180:183], v[72:75]
	v_mfma_f32_16x16x32_bf16 v[124:127], v[132:135], v[176:179], v[124:127]
	v_mfma_f32_16x16x32_bf16 v[116:119], v[140:143], v[176:179], v[116:119]
	v_mfma_f32_16x16x32_bf16 v[108:111], v[132:135], v[172:175], v[108:111]
	v_mfma_f32_16x16x32_bf16 v[100:103], v[140:143], v[172:175], v[100:103]
	v_mfma_f32_16x16x32_bf16 v[92:95], v[132:135], v[168:171], v[92:95]
	v_mfma_f32_16x16x32_bf16 v[84:87], v[140:143], v[168:171], v[84:87]
	v_mfma_f32_16x16x32_bf16 v[76:79], v[132:135], v[164:167], v[76:79]
	v_mfma_f32_16x16x32_bf16 v[68:71], v[140:143], v[164:167], v[68:71]
	v_mfma_f32_16x16x32_bf16 v[124:127], v[136:139], v[192:195], v[124:127]
	v_mfma_f32_16x16x32_bf16 v[116:119], v[144:147], v[192:195], v[116:119]
	v_mfma_f32_16x16x32_bf16 v[108:111], v[136:139], v[188:191], v[108:111]
	v_mfma_f32_16x16x32_bf16 v[100:103], v[144:147], v[188:191], v[100:103]
	v_mfma_f32_16x16x32_bf16 v[92:95], v[136:139], v[184:187], v[92:95]
	v_mfma_f32_16x16x32_bf16 v[84:87], v[144:147], v[184:187], v[84:87]
	v_mfma_f32_16x16x32_bf16 v[76:79], v[136:139], v[180:183], v[76:79]
	v_mfma_f32_16x16x32_bf16 v[68:71], v[144:147], v[180:183], v[68:71]
	s_barrier
	s_and_b64 vcc, exec, s[4:5]
	s_mov_b64 s[88:89], s[86:87]
	s_cbranch_vccnz .LBB0_1615
	ds_read_b128 v[176:179], v241 offset:49152
	ds_read_b128 v[192:195], v241 offset:50176
	ds_read_b128 v[172:175], v241 offset:51200
	ds_read_b128 v[188:191], v241 offset:52224
	ds_read_b128 v[168:171], v241 offset:53248
	ds_read_b128 v[184:187], v241 offset:54272
	ds_read_b128 v[164:167], v241 offset:55296
	ds_read_b128 v[180:183], v241 offset:56320
.LBB0_1615:
	s_mov_b32 m0, s58
	v_lshl_add_u64 v[2:3], v[2:3], 0, s[44:45]
	s_add_u32 s34, s34, 0x80080
	global_load_lds_dwordx4 v[2:3], off
	v_lshl_add_u64 v[2:3], v[218:219], 0, s[44:45]
	s_mov_b32 m0, s59
	s_addc_u32 s35, s35, 0
	global_load_lds_dwordx4 v[2:3], off
	v_lshl_add_u64 v[2:3], s[34:35], 0, v[204:205]
	s_mov_b32 m0, s67
	s_and_b64 vcc, exec, s[4:5]
	global_load_lds_dwordx4 v[2:3], off
	v_lshl_add_u64 v[2:3], s[34:35], 0, v[208:209]
	s_mov_b32 m0, s70
	s_nop 0
	global_load_lds_dwordx4 v[2:3], off
	v_lshl_add_u64 v[2:3], v[220:221], 0, s[44:45]
	s_mov_b32 m0, s60
	s_nop 0
	global_load_lds_dwordx4 v[2:3], off
	v_lshl_add_u64 v[2:3], v[222:223], 0, s[44:45]
	s_mov_b32 m0, s61
	s_nop 0
	global_load_lds_dwordx4 v[2:3], off
	s_waitcnt vmcnt(8)
	s_waitcnt lgkmcnt(0)
	s_barrier
	s_cbranch_vccnz .LBB0_1608
	s_waitcnt lgkmcnt(0)
	v_mfma_f32_16x16x32_bf16 v[64:67], v[148:151], v[176:179], v[64:67]
	v_mfma_f32_16x16x32_bf16 v[56:59], v[156:159], v[176:179], v[56:59]
	v_mfma_f32_16x16x32_bf16 v[48:51], v[148:151], v[172:175], v[48:51]
	v_mfma_f32_16x16x32_bf16 v[40:43], v[156:159], v[172:175], v[40:43]
	v_mfma_f32_16x16x32_bf16 v[32:35], v[148:151], v[168:171], v[32:35]
	v_mfma_f32_16x16x32_bf16 v[24:27], v[156:159], v[168:171], v[24:27]
	v_mfma_f32_16x16x32_bf16 v[16:19], v[148:151], v[164:167], v[16:19]
	v_mfma_f32_16x16x32_bf16 v[8:11], v[156:159], v[164:167], v[8:11]
	v_mfma_f32_16x16x32_bf16 v[64:67], v[152:155], v[192:195], v[64:67]
	v_mfma_f32_16x16x32_bf16 v[56:59], v[160:163], v[192:195], v[56:59]
	v_mfma_f32_16x16x32_bf16 v[48:51], v[152:155], v[188:191], v[48:51]
	v_mfma_f32_16x16x32_bf16 v[40:43], v[160:163], v[188:191], v[40:43]
	v_mfma_f32_16x16x32_bf16 v[32:35], v[152:155], v[184:187], v[32:35]
	v_mfma_f32_16x16x32_bf16 v[24:27], v[160:163], v[184:187], v[24:27]
	v_mfma_f32_16x16x32_bf16 v[16:19], v[152:155], v[180:183], v[16:19]
	v_mfma_f32_16x16x32_bf16 v[8:11], v[160:163], v[180:183], v[8:11]
	v_mfma_f32_16x16x32_bf16 v[60:63], v[132:135], v[176:179], v[60:63]
	v_mfma_f32_16x16x32_bf16 v[52:55], v[140:143], v[176:179], v[52:55]
	v_mfma_f32_16x16x32_bf16 v[44:47], v[132:135], v[172:175], v[44:47]
	v_mfma_f32_16x16x32_bf16 v[36:39], v[140:143], v[172:175], v[36:39]
	v_mfma_f32_16x16x32_bf16 v[28:31], v[132:135], v[168:171], v[28:31]
	v_mfma_f32_16x16x32_bf16 v[20:23], v[140:143], v[168:171], v[20:23]
	v_mfma_f32_16x16x32_bf16 v[12:15], v[132:135], v[164:167], v[12:15]
	v_mfma_f32_16x16x32_bf16 v[2:5], v[140:143], v[164:167], v[4:7]
	v_mfma_f32_16x16x32_bf16 v[60:63], v[136:139], v[192:195], v[60:63]
	v_mfma_f32_16x16x32_bf16 v[52:55], v[144:147], v[192:195], v[52:55]
	v_mfma_f32_16x16x32_bf16 v[44:47], v[136:139], v[188:191], v[44:47]
	v_mfma_f32_16x16x32_bf16 v[36:39], v[144:147], v[188:191], v[36:39]
	v_mfma_f32_16x16x32_bf16 v[28:31], v[136:139], v[184:187], v[28:31]
	v_mfma_f32_16x16x32_bf16 v[20:23], v[144:147], v[184:187], v[20:23]
	v_mfma_f32_16x16x32_bf16 v[12:15], v[136:139], v[180:183], v[12:15]
	v_mfma_f32_16x16x32_bf16 v[4:7], v[144:147], v[180:183], v[2:5]
	s_branch .LBB0_1608

.LBB0_1793:
	v_add_u32_e32 v110, s25, v159
	v_add_u32_e32 v126, s28, v159
	ds_read_b128 v[98:101], v110
	ds_read_b128 v[102:105], v110 offset:1024
	ds_read_b128 v[106:109], v110 offset:2048
	ds_read_b128 v[110:113], v110 offset:3072
	ds_read_b128 v[114:117], v126
	ds_read_b128 v[118:121], v126 offset:1024
	ds_read_b128 v[122:125], v126 offset:2048
	ds_read_b128 v[126:129], v126 offset:3072
	s_add_u32 s4, s8, 0x100
	s_addc_u32 s5, s9, 0
	s_cmpk_eq_i32 s61, 0x54
	s_cselect_b32 s67, s17, s5
	s_cselect_b32 s66, s16, s4
	s_cselect_b32 s21, s19, s60
	s_cselect_b32 s20, s18, s0
	v_lshl_add_u64 v[172:173], s[8:9], 0, v[132:133]
	s_add_i32 m0, s31, 0xc000
	ds_read_b128 v[134:137], v162
	ds_read_b128 v[138:141], v162 offset:1024
	ds_read_b128 v[142:145], v162 offset:2048
	ds_read_b128 v[146:149], v162 offset:3072
	ds_read_b128 v[150:153], v162 offset:4096
	ds_read_b128 v[154:157], v162 offset:5120
	ds_read_b128 v[164:167], v162 offset:6144
	ds_read_b128 v[168:171], v162 offset:7168
	global_load_lds_dwordx4 v[172:173], off
	s_waitcnt vmcnt(7)
	s_waitcnt lgkmcnt(0)
	s_barrier
	s_waitcnt lgkmcnt(0)
	v_mfma_f32_16x16x32_bf16 v[94:97], v[98:101], v[134:137], v[94:97]
	v_mfma_f32_16x16x32_bf16 v[90:93], v[106:109], v[134:137], v[90:93]
	v_mfma_f32_16x16x32_bf16 v[78:81], v[98:101], v[142:145], v[78:81]
	v_mfma_f32_16x16x32_bf16 v[74:77], v[106:109], v[142:145], v[74:77]
	v_mfma_f32_16x16x32_bf16 v[62:65], v[98:101], v[150:153], v[62:65]
	v_mfma_f32_16x16x32_bf16 v[58:61], v[106:109], v[150:153], v[58:61]
	v_mfma_f32_16x16x32_bf16 v[46:49], v[98:101], v[164:167], v[46:49]
	v_mfma_f32_16x16x32_bf16 v[42:45], v[106:109], v[164:167], v[42:45]
	v_mfma_f32_16x16x32_bf16 v[94:97], v[102:105], v[138:141], v[94:97]
	v_mfma_f32_16x16x32_bf16 v[90:93], v[110:113], v[138:141], v[90:93]
	v_mfma_f32_16x16x32_bf16 v[78:81], v[102:105], v[146:149], v[78:81]
	v_mfma_f32_16x16x32_bf16 v[74:77], v[110:113], v[146:149], v[74:77]
	v_mfma_f32_16x16x32_bf16 v[62:65], v[102:105], v[154:157], v[62:65]
	v_mfma_f32_16x16x32_bf16 v[58:61], v[110:113], v[154:157], v[58:61]
	v_mfma_f32_16x16x32_bf16 v[46:49], v[102:105], v[168:171], v[46:49]
	v_mfma_f32_16x16x32_bf16 v[42:45], v[110:113], v[168:171], v[42:45]
	v_mfma_f32_16x16x32_bf16 v[86:89], v[114:117], v[134:137], v[86:89]
	v_mfma_f32_16x16x32_bf16 v[82:85], v[122:125], v[134:137], v[82:85]
	v_mfma_f32_16x16x32_bf16 v[70:73], v[114:117], v[142:145], v[70:73]
	v_mfma_f32_16x16x32_bf16 v[66:69], v[122:125], v[142:145], v[66:69]
	v_mfma_f32_16x16x32_bf16 v[54:57], v[114:117], v[150:153], v[54:57]
	v_mfma_f32_16x16x32_bf16 v[50:53], v[122:125], v[150:153], v[50:53]
	v_mfma_f32_16x16x32_bf16 v[38:41], v[114:117], v[164:167], v[38:41]
	v_mfma_f32_16x16x32_bf16 v[34:37], v[122:125], v[164:167], v[34:37]
	v_mfma_f32_16x16x32_bf16 v[86:89], v[118:121], v[138:141], v[86:89]
	v_mfma_f32_16x16x32_bf16 v[82:85], v[126:129], v[138:141], v[82:85]
	v_mfma_f32_16x16x32_bf16 v[70:73], v[118:121], v[146:149], v[70:73]
	v_mfma_f32_16x16x32_bf16 v[66:69], v[126:129], v[146:149], v[66:69]
	v_mfma_f32_16x16x32_bf16 v[54:57], v[118:121], v[154:157], v[54:57]
	v_mfma_f32_16x16x32_bf16 v[50:53], v[126:129], v[154:157], v[50:53]
	v_mfma_f32_16x16x32_bf16 v[38:41], v[118:121], v[168:171], v[38:41]
	v_mfma_f32_16x16x32_bf16 v[34:37], v[126:129], v[168:171], v[34:37]
	s_barrier
	s_mov_b32 m0, s26
	v_lshl_add_u64 v[172:173], s[20:21], 0, v[0:1]
	s_add_u32 s8, s20, 0x160000
	ds_read_b128 v[134:137], v163 offset:16384
	ds_read_b128 v[138:141], v163 offset:17408
	ds_read_b128 v[142:145], v163 offset:18432
	ds_read_b128 v[146:149], v163 offset:19456
	global_load_lds_dwordx4 v[172:173], off
	v_lshl_add_u64 v[174:175], s[20:21], 0, v[130:131]
	s_mov_b32 m0, s27
	s_addc_u32 s9, s21, 0
	global_load_lds_dwordx4 v[174:175], off
	v_lshl_add_u64 v[150:151], s[8:9], 0, v[0:1]
	s_mov_b32 m0, s29
	v_lshl_add_u64 v[176:177], s[66:67], 0, v[0:1]
	global_load_lds_dwordx4 v[150:151], off
	v_lshl_add_u64 v[150:151], s[8:9], 0, v[130:131]
	s_mov_b32 m0, s30
	v_lshl_add_u64 v[178:179], s[66:67], 0, v[130:131]
	global_load_lds_dwordx4 v[150:151], off
	s_mov_b32 m0, s31
	s_nop 0
	global_load_lds_dwordx4 v[176:177], off
	s_mov_b32 m0, s34
	s_nop 0
	global_load_lds_dwordx4 v[178:179], off
	s_waitcnt vmcnt(7)
	s_waitcnt lgkmcnt(0)
	s_barrier
	s_waitcnt lgkmcnt(0)
	v_mfma_f32_16x16x32_bf16 v[30:33], v[98:101], v[134:137], v[30:33]
	v_mfma_f32_16x16x32_bf16 v[26:29], v[106:109], v[134:137], v[26:29]
	v_mfma_f32_16x16x32_bf16 v[14:17], v[98:101], v[142:145], v[14:17]
	v_mfma_f32_16x16x32_bf16 v[10:13], v[106:109], v[142:145], v[10:13]
	v_mfma_f32_16x16x32_bf16 v[30:33], v[102:105], v[138:141], v[30:33]
	v_mfma_f32_16x16x32_bf16 v[26:29], v[110:113], v[138:141], v[26:29]
	v_mfma_f32_16x16x32_bf16 v[14:17], v[102:105], v[146:149], v[14:17]
	v_mfma_f32_16x16x32_bf16 v[10:13], v[110:113], v[146:149], v[10:13]
	v_mfma_f32_16x16x32_bf16 v[22:25], v[114:117], v[134:137], v[22:25]
	v_mfma_f32_16x16x32_bf16 v[18:21], v[122:125], v[134:137], v[18:21]
	v_mfma_f32_16x16x32_bf16 v[6:9], v[114:117], v[142:145], v[6:9]
	v_mfma_f32_16x16x32_bf16 v[2:5], v[122:125], v[142:145], v[2:5]
	v_mfma_f32_16x16x32_bf16 v[22:25], v[118:121], v[138:141], v[22:25]
	v_mfma_f32_16x16x32_bf16 v[18:21], v[126:129], v[138:141], v[18:21]
	v_mfma_f32_16x16x32_bf16 v[6:9], v[118:121], v[146:149], v[6:9]
	v_mfma_f32_16x16x32_bf16 v[2:5], v[126:129], v[146:149], v[2:5]
	s_barrier
	v_add_u32_e32 v110, s41, v159
	v_add_u32_e32 v126, s51, v159
	ds_read_b128 v[98:101], v110
	ds_read_b128 v[102:105], v110 offset:1024
	ds_read_b128 v[106:109], v110 offset:2048
	ds_read_b128 v[110:113], v110 offset:3072
	ds_read_b128 v[114:117], v126
	ds_read_b128 v[118:121], v126 offset:1024
	ds_read_b128 v[122:125], v126 offset:2048
	ds_read_b128 v[126:129], v126 offset:3072
	v_lshl_add_u64 v[180:181], v[176:177], 0, s[82:83]
	s_mov_b32 m0, s35
	ds_read_b128 v[134:137], v162 offset:32768
	ds_read_b128 v[138:141], v162 offset:33792
	ds_read_b128 v[142:145], v162 offset:34816
	ds_read_b128 v[146:149], v162 offset:35840
	ds_read_b128 v[150:153], v162 offset:36864
	ds_read_b128 v[154:157], v162 offset:37888
	ds_read_b128 v[164:167], v162 offset:38912
	ds_read_b128 v[168:171], v162 offset:39936
	global_load_lds_dwordx4 v[180:181], off
	s_waitcnt vmcnt(7)
	s_waitcnt lgkmcnt(0)
	s_barrier
	s_waitcnt lgkmcnt(0)
	v_mfma_f32_16x16x32_bf16 v[94:97], v[98:101], v[134:137], v[94:97]
	v_mfma_f32_16x16x32_bf16 v[90:93], v[106:109], v[134:137], v[90:93]
	v_mfma_f32_16x16x32_bf16 v[78:81], v[98:101], v[142:145], v[78:81]
	v_mfma_f32_16x16x32_bf16 v[74:77], v[106:109], v[142:145], v[74:77]
	v_mfma_f32_16x16x32_bf16 v[62:65], v[98:101], v[150:153], v[62:65]
	v_mfma_f32_16x16x32_bf16 v[58:61], v[106:109], v[150:153], v[58:61]
	v_mfma_f32_16x16x32_bf16 v[46:49], v[98:101], v[164:167], v[46:49]
	v_mfma_f32_16x16x32_bf16 v[42:45], v[106:109], v[164:167], v[42:45]
	v_mfma_f32_16x16x32_bf16 v[94:97], v[102:105], v[138:141], v[94:97]
	v_mfma_f32_16x16x32_bf16 v[90:93], v[110:113], v[138:141], v[90:93]
	v_mfma_f32_16x16x32_bf16 v[78:81], v[102:105], v[146:149], v[78:81]
	v_mfma_f32_16x16x32_bf16 v[74:77], v[110:113], v[146:149], v[74:77]
	v_mfma_f32_16x16x32_bf16 v[62:65], v[102:105], v[154:157], v[62:65]
	v_mfma_f32_16x16x32_bf16 v[58:61], v[110:113], v[154:157], v[58:61]
	v_mfma_f32_16x16x32_bf16 v[46:49], v[102:105], v[168:171], v[46:49]
	v_mfma_f32_16x16x32_bf16 v[42:45], v[110:113], v[168:171], v[42:45]
	v_mfma_f32_16x16x32_bf16 v[86:89], v[114:117], v[134:137], v[86:89]
	v_mfma_f32_16x16x32_bf16 v[82:85], v[122:125], v[134:137], v[82:85]
	v_mfma_f32_16x16x32_bf16 v[70:73], v[114:117], v[142:145], v[70:73]
	v_mfma_f32_16x16x32_bf16 v[66:69], v[122:125], v[142:145], v[66:69]
	v_mfma_f32_16x16x32_bf16 v[54:57], v[114:117], v[150:153], v[54:57]
	v_mfma_f32_16x16x32_bf16 v[50:53], v[122:125], v[150:153], v[50:53]
	v_mfma_f32_16x16x32_bf16 v[38:41], v[114:117], v[164:167], v[38:41]
	v_mfma_f32_16x16x32_bf16 v[34:37], v[122:125], v[164:167], v[34:37]
	v_mfma_f32_16x16x32_bf16 v[86:89], v[118:121], v[138:141], v[86:89]
	v_mfma_f32_16x16x32_bf16 v[82:85], v[126:129], v[138:141], v[82:85]
	v_mfma_f32_16x16x32_bf16 v[70:73], v[118:121], v[146:149], v[70:73]
	v_mfma_f32_16x16x32_bf16 v[66:69], v[126:129], v[146:149], v[66:69]
	v_mfma_f32_16x16x32_bf16 v[54:57], v[118:121], v[154:157], v[54:57]
	v_mfma_f32_16x16x32_bf16 v[50:53], v[126:129], v[154:157], v[50:53]
	v_mfma_f32_16x16x32_bf16 v[38:41], v[118:121], v[168:171], v[38:41]
	v_mfma_f32_16x16x32_bf16 v[34:37], v[126:129], v[168:171], v[34:37]
	s_barrier
	s_mov_b32 m0, s42
	v_lshl_add_u64 v[150:151], v[172:173], 0, s[44:45]
	s_add_u32 s8, s20, 0x160080
	ds_read_b128 v[134:137], v163 offset:49152
	ds_read_b128 v[138:141], v163 offset:50176
	ds_read_b128 v[142:145], v163 offset:51200
	ds_read_b128 v[146:149], v163 offset:52224
	global_load_lds_dwordx4 v[150:151], off
	v_lshl_add_u64 v[150:151], v[174:175], 0, s[44:45]
	s_mov_b32 m0, s43
	s_addc_u32 s9, s21, 0
	global_load_lds_dwordx4 v[150:151], off
	v_lshl_add_u64 v[150:151], s[8:9], 0, v[0:1]
	s_mov_b32 m0, s52
	s_nop 0
	global_load_lds_dwordx4 v[150:151], off
	v_lshl_add_u64 v[150:151], s[8:9], 0, v[130:131]
	s_mov_b32 m0, s53
	s_nop 0
	global_load_lds_dwordx4 v[150:151], off
	v_lshl_add_u64 v[150:151], v[176:177], 0, s[44:45]
	s_mov_b32 m0, s49
	s_nop 0
	global_load_lds_dwordx4 v[150:151], off
	v_lshl_add_u64 v[150:151], v[178:179], 0, s[44:45]
	s_mov_b32 m0, s50
	s_nop 0
	global_load_lds_dwordx4 v[150:151], off
	s_waitcnt vmcnt(7)
	s_waitcnt lgkmcnt(0)
	s_barrier
	s_waitcnt lgkmcnt(0)
	v_mfma_f32_16x16x32_bf16 v[30:33], v[98:101], v[134:137], v[30:33]
	v_mfma_f32_16x16x32_bf16 v[26:29], v[106:109], v[134:137], v[26:29]
	v_mfma_f32_16x16x32_bf16 v[14:17], v[98:101], v[142:145], v[14:17]
	v_mfma_f32_16x16x32_bf16 v[10:13], v[106:109], v[142:145], v[10:13]
	v_mfma_f32_16x16x32_bf16 v[30:33], v[102:105], v[138:141], v[30:33]
	v_mfma_f32_16x16x32_bf16 v[26:29], v[110:113], v[138:141], v[26:29]
	v_mfma_f32_16x16x32_bf16 v[14:17], v[102:105], v[146:149], v[14:17]
	v_mfma_f32_16x16x32_bf16 v[10:13], v[110:113], v[146:149], v[10:13]
	v_mfma_f32_16x16x32_bf16 v[22:25], v[114:117], v[134:137], v[22:25]
	v_mfma_f32_16x16x32_bf16 v[18:21], v[122:125], v[134:137], v[18:21]
	v_mfma_f32_16x16x32_bf16 v[6:9], v[114:117], v[142:145], v[6:9]
	v_mfma_f32_16x16x32_bf16 v[2:5], v[122:125], v[142:145], v[2:5]
	v_mfma_f32_16x16x32_bf16 v[22:25], v[118:121], v[138:141], v[22:25]
	v_mfma_f32_16x16x32_bf16 v[18:21], v[126:129], v[138:141], v[18:21]
	v_mfma_f32_16x16x32_bf16 v[6:9], v[118:121], v[146:149], v[6:9]
	v_mfma_f32_16x16x32_bf16 v[2:5], v[126:129], v[146:149], v[2:5]
	s_barrier
	s_add_i32 s61, s61, 2
	s_add_u32 s0, s0, 0x100
	s_addc_u32 s60, s60, 0
	s_cmpk_gt_u32 s61, 0x55
	s_mov_b64 s[8:9], s[4:5]
	s_cbranch_scc0 .LBB0_1793
	s_and_b64 vcc, exec, s[14:15]
	s_cbranch_vccz .LBB0_1796
	s_barrier
